# residual-add GEMM epilogue: wait before second-half math relaxed from vmcnt(0) to vmcnt(8) (only the older residual loads are needed, not the first-half stores)
# baseline (speedup 1.0000x reference)
.LBB0_31:
	s_add_u32 s46, s50, 0x100
	s_addc_u32 s47, s51, 0
	s_add_i32 s6, 0, 0x10000
	v_add_u32_e32 v146, s6, v206
	ds_read_b128 v[128:131], v146
	ds_read_b128 v[132:135], v146 offset:1024
	ds_read_b128 v[136:139], v146 offset:2048
	ds_read_b128 v[146:149], v146 offset:3072
	s_cmp_eq_u32 s12, 40
	s_cselect_b32 s53, s31, s47
	s_cselect_b32 s52, s30, s46
	s_cselect_b32 s49, s35, s11
	s_cselect_b32 s48, s34, s10
	v_lshl_add_u64 v[214:215], s[50:51], 0, v[158:159]
	s_add_i32 m0, s58, 0xc000
	ds_read_b128 v[162:165], v208
	ds_read_b128 v[166:169], v208 offset:1024
	ds_read_b128 v[170:173], v208 offset:2048
	ds_read_b128 v[174:177], v208 offset:3072
	ds_read_b128 v[178:181], v208 offset:4096
	ds_read_b128 v[182:185], v208 offset:5120
	ds_read_b128 v[194:197], v208 offset:6144
	ds_read_b128 v[210:213], v208 offset:7168
	global_load_lds_dwordx4 v[214:215], off
	v_lshl_add_u64 v[214:215], s[50:51], 0, v[160:161]
	s_add_i32 m0, s58, 0xe000
	s_nop 0
	global_load_lds_dwordx4 v[214:215], off
	s_add_i32 s19, 0, 0x14000
	v_add_u32_e32 v192, s19, v206
	ds_read_b128 v[214:217], v192
	ds_read_b128 v[218:221], v192 offset:1024
	ds_read_b128 v[222:225], v192 offset:2048
	ds_read_b128 v[226:229], v192 offset:3072
	s_waitcnt vmcnt(8)
	s_waitcnt lgkmcnt(0)
	s_barrier
	v_mfma_f32_16x16x32_bf16 v[124:127], v[128:131], v[162:165], v[124:127]
	v_mfma_f32_16x16x32_bf16 v[120:123], v[136:139], v[162:165], v[120:123]
	v_mfma_f32_16x16x32_bf16 v[108:111], v[128:131], v[170:173], v[108:111]
	v_mfma_f32_16x16x32_bf16 v[104:107], v[136:139], v[170:173], v[104:107]
	v_mfma_f32_16x16x32_bf16 v[96:99], v[128:131], v[178:181], v[96:99]
	v_mfma_f32_16x16x32_bf16 v[88:91], v[136:139], v[178:181], v[88:91]
	v_mfma_f32_16x16x32_bf16 v[84:87], v[128:131], v[194:197], v[84:87]
	v_mfma_f32_16x16x32_bf16 v[80:83], v[136:139], v[194:197], v[80:83]
	v_mfma_f32_16x16x32_bf16 v[124:127], v[132:135], v[166:169], v[124:127]
	v_mfma_f32_16x16x32_bf16 v[120:123], v[146:149], v[166:169], v[120:123]
	v_mfma_f32_16x16x32_bf16 v[108:111], v[132:135], v[174:177], v[108:111]
	v_mfma_f32_16x16x32_bf16 v[104:107], v[146:149], v[174:177], v[104:107]
	v_mfma_f32_16x16x32_bf16 v[96:99], v[132:135], v[182:185], v[96:99]
	v_mfma_f32_16x16x32_bf16 v[88:91], v[146:149], v[182:185], v[88:91]
	v_mfma_f32_16x16x32_bf16 v[84:87], v[132:135], v[210:213], v[84:87]
	v_mfma_f32_16x16x32_bf16 v[80:83], v[146:149], v[210:213], v[80:83]
	v_mfma_f32_16x16x32_bf16 v[116:119], v[214:217], v[162:165], v[116:119]
	v_mfma_f32_16x16x32_bf16 v[112:115], v[222:225], v[162:165], v[112:115]
	v_mfma_f32_16x16x32_bf16 v[100:103], v[214:217], v[170:173], v[100:103]
	v_mfma_f32_16x16x32_bf16 v[92:95], v[222:225], v[170:173], v[92:95]
	v_mfma_f32_16x16x32_bf16 v[76:79], v[214:217], v[178:181], v[76:79]
	v_mfma_f32_16x16x32_bf16 v[72:75], v[222:225], v[178:181], v[72:75]
	v_mfma_f32_16x16x32_bf16 v[68:71], v[214:217], v[194:197], v[68:71]
	v_mfma_f32_16x16x32_bf16 v[64:67], v[222:225], v[194:197], v[64:67]
	v_mfma_f32_16x16x32_bf16 v[116:119], v[218:221], v[166:169], v[116:119]
	v_mfma_f32_16x16x32_bf16 v[112:115], v[226:229], v[166:169], v[112:115]
	v_mfma_f32_16x16x32_bf16 v[100:103], v[218:221], v[174:177], v[100:103]
	v_mfma_f32_16x16x32_bf16 v[92:95], v[226:229], v[174:177], v[92:95]
	v_mfma_f32_16x16x32_bf16 v[76:79], v[218:221], v[182:185], v[76:79]
	v_mfma_f32_16x16x32_bf16 v[72:75], v[226:229], v[182:185], v[72:75]
	v_mfma_f32_16x16x32_bf16 v[68:71], v[218:221], v[210:213], v[68:71]
	v_mfma_f32_16x16x32_bf16 v[64:67], v[226:229], v[210:213], v[64:67]
	s_barrier
	s_add_i32 s6, s6, s57
	v_lshl_add_u64 v[230:231], s[48:49], 0, v[140:141]
	s_mov_b32 m0, s6
	s_nop 0
	global_load_lds_dwordx4 v[230:231], off
	v_lshl_add_u64 v[232:233], s[48:49], 0, v[150:151]
	s_add_i32 m0, s6, 0x2000
	s_nop 0
	global_load_lds_dwordx4 v[232:233], off
	s_mov_b32 m0, s58
	v_lshl_add_u64 v[234:235], s[52:53], 0, v[154:155]
	ds_read_b128 v[162:165], v208 offset:16384
	ds_read_b128 v[166:169], v208 offset:17408
	ds_read_b128 v[170:173], v208 offset:18432
	ds_read_b128 v[174:177], v208 offset:19456
	ds_read_b128 v[178:181], v208 offset:20480
	ds_read_b128 v[182:185], v208 offset:21504
	ds_read_b128 v[194:197], v208 offset:22528
	ds_read_b128 v[210:213], v208 offset:23552
	global_load_lds_dwordx4 v[234:235], off
	v_lshl_add_u64 v[236:237], s[52:53], 0, v[152:153]
	s_mov_b32 m0, s59
	s_nop 0
	global_load_lds_dwordx4 v[236:237], off
	s_add_u32 s50, s48, 0xb0000
	s_addc_u32 s51, s49, 0
	s_add_i32 s6, s19, s57
	v_lshl_add_u64 v[250:251], s[50:51], 0, v[140:141]
	s_mov_b32 m0, s6
	s_nop 0
	global_load_lds_dwordx4 v[250:251], off
	v_lshl_add_u64 v[250:251], s[50:51], 0, v[150:151]
	s_add_i32 m0, s6, 0x2000
	s_nop 0
	global_load_lds_dwordx4 v[250:251], off
	s_waitcnt vmcnt(8)
	s_waitcnt lgkmcnt(0)
	s_barrier
	v_mfma_f32_16x16x32_bf16 v[60:63], v[128:131], v[162:165], v[60:63]
	v_mfma_f32_16x16x32_bf16 v[56:59], v[136:139], v[162:165], v[56:59]
	v_mfma_f32_16x16x32_bf16 v[48:51], v[128:131], v[170:173], v[48:51]
	v_mfma_f32_16x16x32_bf16 v[40:43], v[136:139], v[170:173], v[40:43]
	v_mfma_f32_16x16x32_bf16 v[32:35], v[128:131], v[178:181], v[32:35]
	v_mfma_f32_16x16x32_bf16 v[24:27], v[136:139], v[178:181], v[24:27]
	v_mfma_f32_16x16x32_bf16 v[16:19], v[128:131], v[194:197], v[16:19]
	v_mfma_f32_16x16x32_bf16 v[8:11], v[136:139], v[194:197], v[8:11]
	v_mfma_f32_16x16x32_bf16 v[60:63], v[132:135], v[166:169], v[60:63]
	v_mfma_f32_16x16x32_bf16 v[56:59], v[146:149], v[166:169], v[56:59]
	v_mfma_f32_16x16x32_bf16 v[48:51], v[132:135], v[174:177], v[48:51]
	v_mfma_f32_16x16x32_bf16 v[40:43], v[146:149], v[174:177], v[40:43]
	v_mfma_f32_16x16x32_bf16 v[32:35], v[132:135], v[182:185], v[32:35]
	v_mfma_f32_16x16x32_bf16 v[24:27], v[146:149], v[182:185], v[24:27]
	v_mfma_f32_16x16x32_bf16 v[16:19], v[132:135], v[210:213], v[16:19]
	v_mfma_f32_16x16x32_bf16 v[8:11], v[146:149], v[210:213], v[8:11]
	v_mfma_f32_16x16x32_bf16 v[52:55], v[214:217], v[162:165], v[52:55]
	v_mfma_f32_16x16x32_bf16 v[44:47], v[222:225], v[162:165], v[44:47]
	v_mfma_f32_16x16x32_bf16 v[36:39], v[214:217], v[170:173], v[36:39]
	v_mfma_f32_16x16x32_bf16 v[28:31], v[222:225], v[170:173], v[28:31]
	v_mfma_f32_16x16x32_bf16 v[20:23], v[214:217], v[178:181], v[20:23]
	v_mfma_f32_16x16x32_bf16 v[12:15], v[222:225], v[178:181], v[12:15]
	v_mfma_f32_16x16x32_bf16 v[4:7], v[214:217], v[194:197], v[4:7]
	v_mfma_f32_16x16x32_bf16 v[0:3], v[222:225], v[194:197], v[0:3]
	v_mfma_f32_16x16x32_bf16 v[52:55], v[218:221], v[166:169], v[52:55]
	v_mfma_f32_16x16x32_bf16 v[44:47], v[226:229], v[166:169], v[44:47]
	v_mfma_f32_16x16x32_bf16 v[36:39], v[218:221], v[174:177], v[36:39]
	v_mfma_f32_16x16x32_bf16 v[28:31], v[226:229], v[174:177], v[28:31]
	v_mfma_f32_16x16x32_bf16 v[20:23], v[218:221], v[182:185], v[20:23]
	v_mfma_f32_16x16x32_bf16 v[12:15], v[226:229], v[182:185], v[12:15]
	v_mfma_f32_16x16x32_bf16 v[4:7], v[218:221], v[210:213], v[4:7]
	v_mfma_f32_16x16x32_bf16 v[0:3], v[226:229], v[210:213], v[0:3]
	s_barrier
	s_add_i32 s6, 0, 0x18000
	v_add_u32_e32 v146, s6, v206
	ds_read_b128 v[128:131], v146
	ds_read_b128 v[132:135], v146 offset:1024
	ds_read_b128 v[136:139], v146 offset:2048
	ds_read_b128 v[146:149], v146 offset:3072
	s_add_u32 s50, s52, 0xb0000
	s_addc_u32 s51, s53, 0
	s_mov_b32 m0, s68
	v_lshl_add_u64 v[214:215], s[50:51], 0, v[154:155]
	ds_read_b128 v[162:165], v208 offset:32768
	ds_read_b128 v[166:169], v208 offset:33792
	ds_read_b128 v[170:173], v208 offset:34816
	ds_read_b128 v[174:177], v208 offset:35840
	ds_read_b128 v[178:181], v208 offset:36864
	ds_read_b128 v[182:185], v208 offset:37888
	ds_read_b128 v[194:197], v208 offset:38912
	ds_read_b128 v[210:213], v208 offset:39936
	global_load_lds_dwordx4 v[214:215], off
	v_lshl_add_u64 v[214:215], s[50:51], 0, v[152:153]
	s_mov_b32 m0, s69
	s_nop 0
	global_load_lds_dwordx4 v[214:215], off
	s_add_i32 s19, 0, 0x1c000
	v_add_u32_e32 v192, s19, v206
	ds_read_b128 v[214:217], v192
	ds_read_b128 v[218:221], v192 offset:1024
	ds_read_b128 v[222:225], v192 offset:2048
	ds_read_b128 v[226:229], v192 offset:3072
	s_waitcnt vmcnt(8)
	s_waitcnt lgkmcnt(0)
	s_barrier
	v_mfma_f32_16x16x32_bf16 v[124:127], v[128:131], v[162:165], v[124:127]
	v_mfma_f32_16x16x32_bf16 v[120:123], v[136:139], v[162:165], v[120:123]
	v_mfma_f32_16x16x32_bf16 v[108:111], v[128:131], v[170:173], v[108:111]
	v_mfma_f32_16x16x32_bf16 v[104:107], v[136:139], v[170:173], v[104:107]
	v_mfma_f32_16x16x32_bf16 v[96:99], v[128:131], v[178:181], v[96:99]
	v_mfma_f32_16x16x32_bf16 v[88:91], v[136:139], v[178:181], v[88:91]
	v_mfma_f32_16x16x32_bf16 v[84:87], v[128:131], v[194:197], v[84:87]
	v_mfma_f32_16x16x32_bf16 v[80:83], v[136:139], v[194:197], v[80:83]
	v_mfma_f32_16x16x32_bf16 v[124:127], v[132:135], v[166:169], v[124:127]
	v_mfma_f32_16x16x32_bf16 v[120:123], v[146:149], v[166:169], v[120:123]
	v_mfma_f32_16x16x32_bf16 v[108:111], v[132:135], v[174:177], v[108:111]
	v_mfma_f32_16x16x32_bf16 v[104:107], v[146:149], v[174:177], v[104:107]
	v_mfma_f32_16x16x32_bf16 v[96:99], v[132:135], v[182:185], v[96:99]
	v_mfma_f32_16x16x32_bf16 v[88:91], v[146:149], v[182:185], v[88:91]
	v_mfma_f32_16x16x32_bf16 v[84:87], v[132:135], v[210:213], v[84:87]
	v_mfma_f32_16x16x32_bf16 v[80:83], v[146:149], v[210:213], v[80:83]
	v_mfma_f32_16x16x32_bf16 v[116:119], v[214:217], v[162:165], v[116:119]
	v_mfma_f32_16x16x32_bf16 v[112:115], v[222:225], v[162:165], v[112:115]
	v_mfma_f32_16x16x32_bf16 v[100:103], v[214:217], v[170:173], v[100:103]
	v_mfma_f32_16x16x32_bf16 v[92:95], v[222:225], v[170:173], v[92:95]
	v_mfma_f32_16x16x32_bf16 v[76:79], v[214:217], v[178:181], v[76:79]
	v_mfma_f32_16x16x32_bf16 v[72:75], v[222:225], v[178:181], v[72:75]
	v_mfma_f32_16x16x32_bf16 v[68:71], v[214:217], v[194:197], v[68:71]
	v_mfma_f32_16x16x32_bf16 v[64:67], v[222:225], v[194:197], v[64:67]
	v_mfma_f32_16x16x32_bf16 v[116:119], v[218:221], v[166:169], v[116:119]
	v_mfma_f32_16x16x32_bf16 v[112:115], v[226:229], v[166:169], v[112:115]
	v_mfma_f32_16x16x32_bf16 v[100:103], v[218:221], v[174:177], v[100:103]
	v_mfma_f32_16x16x32_bf16 v[92:95], v[226:229], v[174:177], v[92:95]
	v_mfma_f32_16x16x32_bf16 v[76:79], v[218:221], v[182:185], v[76:79]
	v_mfma_f32_16x16x32_bf16 v[72:75], v[226:229], v[182:185], v[72:75]
	v_mfma_f32_16x16x32_bf16 v[68:71], v[218:221], v[210:213], v[68:71]
	v_mfma_f32_16x16x32_bf16 v[64:67], v[226:229], v[210:213], v[64:67]
	s_barrier
	s_add_i32 s6, s6, s57
	v_lshl_add_u64 v[230:231], v[230:231], 0, s[36:37]
	s_mov_b32 m0, s6
	s_nop 0
	global_load_lds_dwordx4 v[230:231], off
	v_lshl_add_u64 v[230:231], v[232:233], 0, s[36:37]
	s_add_i32 m0, s6, 0x2000
	s_nop 0
	global_load_lds_dwordx4 v[230:231], off
	s_mov_b32 m0, s70
	v_lshl_add_u64 v[230:231], v[234:235], 0, s[36:37]
	ds_read_b128 v[162:165], v208 offset:49152
	ds_read_b128 v[166:169], v208 offset:50176
	ds_read_b128 v[170:173], v208 offset:51200
	ds_read_b128 v[174:177], v208 offset:52224
	ds_read_b128 v[178:181], v208 offset:53248
	ds_read_b128 v[182:185], v208 offset:54272
	ds_read_b128 v[194:197], v208 offset:55296
	ds_read_b128 v[210:213], v208 offset:56320
	global_load_lds_dwordx4 v[230:231], off
	v_lshl_add_u64 v[230:231], v[236:237], 0, s[36:37]
	s_mov_b32 m0, s71
	s_nop 0
	global_load_lds_dwordx4 v[230:231], off
	s_add_u32 s48, s48, 0xb0080
	s_addc_u32 s49, s49, 0
	s_add_i32 s6, s19, s57
	v_lshl_add_u64 v[250:251], s[48:49], 0, v[140:141]
	s_mov_b32 m0, s6
	s_nop 0
	global_load_lds_dwordx4 v[250:251], off
	v_lshl_add_u64 v[250:251], s[48:49], 0, v[150:151]
	s_add_i32 m0, s6, 0x2000
	s_nop 0
	global_load_lds_dwordx4 v[250:251], off
	s_waitcnt vmcnt(8)
	s_waitcnt lgkmcnt(0)
	s_barrier
	v_mfma_f32_16x16x32_bf16 v[60:63], v[128:131], v[162:165], v[60:63]
	v_mfma_f32_16x16x32_bf16 v[56:59], v[136:139], v[162:165], v[56:59]
	v_mfma_f32_16x16x32_bf16 v[48:51], v[128:131], v[170:173], v[48:51]
	v_mfma_f32_16x16x32_bf16 v[40:43], v[136:139], v[170:173], v[40:43]
	v_mfma_f32_16x16x32_bf16 v[32:35], v[128:131], v[178:181], v[32:35]
	v_mfma_f32_16x16x32_bf16 v[24:27], v[136:139], v[178:181], v[24:27]
	v_mfma_f32_16x16x32_bf16 v[16:19], v[128:131], v[194:197], v[16:19]
	v_mfma_f32_16x16x32_bf16 v[8:11], v[136:139], v[194:197], v[8:11]
	v_mfma_f32_16x16x32_bf16 v[60:63], v[132:135], v[166:169], v[60:63]
	v_mfma_f32_16x16x32_bf16 v[56:59], v[146:149], v[166:169], v[56:59]
	v_mfma_f32_16x16x32_bf16 v[48:51], v[132:135], v[174:177], v[48:51]
	v_mfma_f32_16x16x32_bf16 v[40:43], v[146:149], v[174:177], v[40:43]
	v_mfma_f32_16x16x32_bf16 v[32:35], v[132:135], v[182:185], v[32:35]
	v_mfma_f32_16x16x32_bf16 v[24:27], v[146:149], v[182:185], v[24:27]
	v_mfma_f32_16x16x32_bf16 v[16:19], v[132:135], v[210:213], v[16:19]
	v_mfma_f32_16x16x32_bf16 v[8:11], v[146:149], v[210:213], v[8:11]
	v_mfma_f32_16x16x32_bf16 v[52:55], v[214:217], v[162:165], v[52:55]
	v_mfma_f32_16x16x32_bf16 v[44:47], v[222:225], v[162:165], v[44:47]
	v_mfma_f32_16x16x32_bf16 v[36:39], v[214:217], v[170:173], v[36:39]
	v_mfma_f32_16x16x32_bf16 v[28:31], v[222:225], v[170:173], v[28:31]
	v_mfma_f32_16x16x32_bf16 v[20:23], v[214:217], v[178:181], v[20:23]
	v_mfma_f32_16x16x32_bf16 v[12:15], v[222:225], v[178:181], v[12:15]
	v_mfma_f32_16x16x32_bf16 v[4:7], v[214:217], v[194:197], v[4:7]
	v_mfma_f32_16x16x32_bf16 v[0:3], v[222:225], v[194:197], v[0:3]
	v_mfma_f32_16x16x32_bf16 v[52:55], v[218:221], v[166:169], v[52:55]
	v_mfma_f32_16x16x32_bf16 v[44:47], v[226:229], v[166:169], v[44:47]
	v_mfma_f32_16x16x32_bf16 v[36:39], v[218:221], v[174:177], v[36:39]
	v_mfma_f32_16x16x32_bf16 v[28:31], v[226:229], v[174:177], v[28:31]
	v_mfma_f32_16x16x32_bf16 v[20:23], v[218:221], v[182:185], v[20:23]
	v_mfma_f32_16x16x32_bf16 v[12:15], v[226:229], v[182:185], v[12:15]
	v_mfma_f32_16x16x32_bf16 v[4:7], v[218:221], v[210:213], v[4:7]
	v_mfma_f32_16x16x32_bf16 v[0:3], v[226:229], v[210:213], v[0:3]
	s_add_i32 s12, s12, 2
	s_add_u32 s10, s10, 0x100
	s_addc_u32 s11, s11, 0
	s_cmp_gt_u32 s12, 41
	s_mov_b64 s[50:51], s[46:47]
	s_barrier
	s_cbranch_scc0 .LBB0_31
	s_mov_b32 s100, 1
	s_ashr_i32 s39, s38, 31
	v_lshl_or_b32 v128, s81, 8, v207
	s_lshl_b64 s[10:11], s[38:39], 8
	v_ashrrev_i32_e32 v129, 31, v128
	v_lshl_add_u64 v[168:169], s[10:11], 0, v[156:157]
	v_lshlrev_b64 v[170:171], 1, v[128:129]
	v_lshl_add_u64 v[174:175], s[4:5], 0, v[170:171]
	v_lshlrev_b64 v[172:173], 11, v[168:169]
	v_lshl_add_u64 v[128:129], v[174:175], 0, v[172:173]
	global_load_dwordx4 v[146:149], v[128:129], off
	global_load_dwordx4 v[182:185], v[128:129], off offset:256
	v_or_b32_e32 v166, 16, v168
	v_mov_b32_e32 v167, v169
	v_lshlrev_b64 v[176:177], 11, v[166:167]
	v_lshl_add_u64 v[128:129], v[174:175], 0, v[176:177]
	global_load_dwordx4 v[194:197], v[128:129], off
	global_load_dwordx4 v[210:213], v[128:129], off offset:256
	v_or_b32_e32 v164, 32, v168
	v_mov_b32_e32 v165, v169
	v_or_b32_e32 v162, 48, v168
	v_mov_b32_e32 v163, v169
	v_lshlrev_b64 v[180:181], 11, v[164:165]
	v_lshlrev_b64 v[178:179], 11, v[162:163]
	v_lshl_add_u64 v[128:129], v[174:175], 0, v[180:181]
	v_lshl_add_u64 v[130:131], v[174:175], 0, v[178:179]
	global_load_dwordx4 v[214:217], v[128:129], off
	global_load_dwordx4 v[136:139], v[128:129], off offset:256
	global_load_dwordx4 v[132:135], v[130:131], off
	s_nop 0
	global_load_dwordx4 v[128:131], v[130:131], off offset:256
	s_mov_b64 s[10:11], 0x90
	v_lshl_add_u64 v[172:173], s[28:29], 0, v[172:173]
	v_lshl_add_u64 v[172:173], v[172:173], 0, v[170:171]
	s_waitcnt vmcnt(0)
	v_lshlrev_b32_e32 v218, 16, v146
	v_and_b32_e32 v219, 0xffff0000, v146
	v_lshlrev_b32_e32 v220, 16, v148
	v_and_b32_e32 v221, 0xffff0000, v148
	v_lshlrev_b32_e32 v146, 16, v147
	v_and_b32_e32 v147, 0xffff0000, v147
	v_lshlrev_b32_e32 v222, 16, v182
	v_and_b32_e32 v223, 0xffff0000, v182
	v_lshlrev_b32_e32 v224, 16, v184
	v_and_b32_e32 v225, 0xffff0000, v184
	v_lshlrev_b32_e32 v182, 16, v183
	v_and_b32_e32 v183, 0xffff0000, v183
	v_pk_fma_f32 v[124:125], v[124:125], 0.5, v[218:219] op_sel_hi:[1,0,1]
	v_pk_fma_f32 v[120:121], v[120:121], 0.5, v[220:221] op_sel_hi:[1,0,1]
	v_pk_fma_f32 v[126:127], v[126:127], 0.5, v[146:147] op_sel_hi:[1,0,1]
	v_pk_fma_f32 v[116:117], v[116:117], 0.5, v[222:223] op_sel_hi:[1,0,1]
	v_pk_fma_f32 v[146:147], v[112:113], 0.5, v[224:225] op_sel_hi:[1,0,1]
	v_pk_fma_f32 v[118:119], v[118:119], 0.5, v[182:183] op_sel_hi:[1,0,1]
	v_pk_mul_f32 v[220:221], v[124:125], v[124:125]
	v_pk_mul_f32 v[222:223], v[126:127], v[126:127]
	v_cvt_pk_bf16_f32 v112, v124, v125
	v_cvt_pk_bf16_f32 v113, v126, v127
	v_pk_mul_f32 v[124:125], v[116:117], v[116:117]
	v_pk_mul_f32 v[126:127], v[118:119], v[118:119]
	v_pk_mul_f32 v[228:229], v[146:147], v[146:147]
	v_cvt_pk_bf16_f32 v116, v116, v117
	v_cvt_pk_bf16_f32 v117, v118, v119
	v_cvt_pk_bf16_f32 v118, v146, v147
	v_add_f32_e32 v146, v220, v221
	v_add_f32_e32 v146, v222, v146
	v_lshlrev_b32_e32 v148, 16, v149
	v_and_b32_e32 v149, 0xffff0000, v149
	v_pk_mul_f32 v[224:225], v[120:121], v[120:121]
	v_add_f32_e32 v146, v223, v146
	v_pk_fma_f32 v[122:123], v[122:123], 0.5, v[148:149] op_sel_hi:[1,0,1]
	v_add_f32_e32 v146, v224, v146
	v_pk_mul_f32 v[226:227], v[122:123], v[122:123]
	v_add_f32_e32 v146, v225, v146
	v_add_f32_e32 v146, v226, v146
	v_add_f32_e32 v146, v227, v146
	v_add_f32_e32 v124, v124, v146
	v_add_f32_e32 v124, v125, v124
	v_add_f32_e32 v124, v126, v124
	v_lshlrev_b32_e32 v184, 16, v185
	v_and_b32_e32 v185, 0xffff0000, v185
	v_add_f32_e32 v124, v127, v124
	v_pk_fma_f32 v[148:149], v[114:115], 0.5, v[184:185] op_sel_hi:[1,0,1]
	v_add_f32_e32 v124, v228, v124
	v_pk_mul_f32 v[230:231], v[148:149], v[148:149]
	v_add_f32_e32 v124, v229, v124
	v_add_f32_e32 v124, v230, v124
	v_add_f32_e32 v209, v231, v124
	v_lshlrev_b32_e32 v124, 16, v212
	v_and_b32_e32 v125, 0xffff0000, v212
	v_pk_fma_f32 v[124:125], v[92:93], 0.5, v[124:125] op_sel_hi:[1,0,1]
	v_lshlrev_b32_e32 v92, 16, v211
	v_and_b32_e32 v93, 0xffff0000, v211
	v_pk_fma_f32 v[102:103], v[102:103], 0.5, v[92:93] op_sel_hi:[1,0,1]
	v_lshlrev_b32_e32 v92, 16, v213
	v_and_b32_e32 v93, 0xffff0000, v213
	v_pk_fma_f32 v[126:127], v[94:95], 0.5, v[92:93] op_sel_hi:[1,0,1]
	v_lshlrev_b32_e32 v92, 16, v214
	v_and_b32_e32 v93, 0xffff0000, v214
	v_pk_fma_f32 v[92:93], v[96:97], 0.5, v[92:93] op_sel_hi:[1,0,1]
	v_lshlrev_b32_e32 v96, 16, v217
	v_and_b32_e32 v97, 0xffff0000, v217
	v_lshlrev_b32_e32 v94, 16, v216
	v_and_b32_e32 v95, 0xffff0000, v216
	v_pk_fma_f32 v[90:91], v[90:91], 0.5, v[96:97] op_sel_hi:[1,0,1]
	v_lshlrev_b32_e32 v96, 16, v136
	v_and_b32_e32 v97, 0xffff0000, v136
	v_lshlrev_b32_e32 v182, 16, v194
	v_and_b32_e32 v183, 0xffff0000, v194
	v_pk_fma_f32 v[88:89], v[88:89], 0.5, v[94:95] op_sel_hi:[1,0,1]
	v_lshlrev_b32_e32 v94, 16, v215
	v_and_b32_e32 v95, 0xffff0000, v215
	v_pk_fma_f32 v[96:97], v[76:77], 0.5, v[96:97] op_sel_hi:[1,0,1]
	v_lshl_add_u64 v[76:77], v[168:169], 0, s[36:37]
	v_lshlrev_b32_e32 v184, 16, v196
	v_and_b32_e32 v185, 0xffff0000, v196
	v_cvt_pk_bf16_f32 v114, v120, v121
	v_pk_fma_f32 v[120:121], v[108:109], 0.5, v[182:183] op_sel_hi:[1,0,1]
	v_pk_fma_f32 v[94:95], v[98:99], 0.5, v[94:95] op_sel_hi:[1,0,1]
	v_lshlrev_b64 v[182:183], 11, v[76:77]
	v_lshlrev_b32_e32 v98, 16, v138
	v_and_b32_e32 v99, 0xffff0000, v138
	v_pk_fma_f32 v[108:109], v[104:105], 0.5, v[184:185] op_sel_hi:[1,0,1]
	v_lshl_add_u64 v[184:185], v[174:175], 0, v[182:183]
	v_pk_fma_f32 v[98:99], v[72:73], 0.5, v[98:99] op_sel_hi:[1,0,1]
	v_lshlrev_b32_e32 v72, 16, v137
	v_and_b32_e32 v73, 0xffff0000, v137
	v_lshlrev_b32_e32 v218, 16, v210
	v_and_b32_e32 v219, 0xffff0000, v210
	global_load_dwordx4 v[210:213], v[184:185], off
	v_pk_fma_f32 v[136:137], v[78:79], 0.5, v[72:73] op_sel_hi:[1,0,1]
	v_lshlrev_b32_e32 v72, 16, v139
	v_and_b32_e32 v73, 0xffff0000, v139
	v_pk_fma_f32 v[138:139], v[74:75], 0.5, v[72:73] op_sel_hi:[1,0,1]
	v_lshlrev_b32_e32 v72, 16, v132
	v_and_b32_e32 v73, 0xffff0000, v132
	v_pk_fma_f32 v[74:75], v[84:85], 0.5, v[72:73] op_sel_hi:[1,0,1]
	v_lshlrev_b32_e32 v72, 16, v134
	v_and_b32_e32 v73, 0xffff0000, v134
	v_pk_fma_f32 v[78:79], v[80:81], 0.5, v[72:73] op_sel_hi:[1,0,1]
	v_lshlrev_b32_e32 v72, 16, v133
	v_and_b32_e32 v73, 0xffff0000, v133
	v_pk_fma_f32 v[100:101], v[100:101], 0.5, v[218:219] op_sel_hi:[1,0,1]
	global_load_dwordx4 v[218:221], v[184:185], off offset:256
	v_pk_fma_f32 v[80:81], v[86:87], 0.5, v[72:73] op_sel_hi:[1,0,1]
	v_lshlrev_b32_e32 v72, 16, v135
	v_and_b32_e32 v73, 0xffff0000, v135
	v_pk_fma_f32 v[82:83], v[82:83], 0.5, v[72:73] op_sel_hi:[1,0,1]
	v_lshl_add_u64 v[72:73], v[168:169], 0, s[10:11]
	v_lshlrev_b64 v[132:133], 11, v[72:73]
	v_lshl_add_u64 v[134:135], v[174:175], 0, v[132:133]
	v_lshlrev_b32_e32 v84, 16, v128
	v_and_b32_e32 v85, 0xffff0000, v128
	global_load_dwordx4 v[226:229], v[134:135], off
	global_load_dwordx4 v[234:237], v[134:135], off offset:256
	v_pk_fma_f32 v[84:85], v[68:69], 0.5, v[84:85] op_sel_hi:[1,0,1]
	v_lshlrev_b32_e32 v68, 16, v130
	v_and_b32_e32 v69, 0xffff0000, v130
	v_pk_fma_f32 v[86:87], v[64:65], 0.5, v[68:69] op_sel_hi:[1,0,1]
	v_lshlrev_b32_e32 v64, 16, v129
	v_and_b32_e32 v65, 0xffff0000, v129
	s_mov_b64 s[10:11], 0xa0
	v_pk_fma_f32 v[128:129], v[70:71], 0.5, v[64:65] op_sel_hi:[1,0,1]
	v_lshl_add_u64 v[70:71], v[168:169], 0, s[10:11]
	s_mov_b64 s[10:11], 0xb0
	v_lshlrev_b32_e32 v64, 16, v131
	v_and_b32_e32 v65, 0xffff0000, v131
	v_lshlrev_b64 v[134:135], 11, v[70:71]
	v_lshl_add_u64 v[68:69], v[168:169], 0, s[10:11]
	v_pk_fma_f32 v[130:131], v[66:67], 0.5, v[64:65] op_sel_hi:[1,0,1]
	v_lshl_add_u64 v[64:65], v[174:175], 0, v[134:135]
	v_lshlrev_b64 v[184:185], 11, v[68:69]
	global_load_dwordx4 v[238:241], v[64:65], off
	global_load_dwordx4 v[242:245], v[64:65], off offset:256
	v_lshl_add_u64 v[64:65], v[174:175], 0, v[184:185]
	global_load_dwordx4 v[246:249], v[64:65], off
	s_nop 0
	global_load_dwordx4 v[64:67], v[64:65], off offset:256
	v_lshlrev_b32_e32 v194, 16, v195
	v_and_b32_e32 v195, 0xffff0000, v195
	v_lshlrev_b32_e32 v196, 16, v197
	v_and_b32_e32 v197, 0xffff0000, v197
	v_cvt_pk_bf16_f32 v115, v122, v123
	v_cvt_pk_bf16_f32 v119, v148, v149
	v_pk_fma_f32 v[122:123], v[110:111], 0.5, v[194:195] op_sel_hi:[1,0,1]
	v_pk_fma_f32 v[110:111], v[106:107], 0.5, v[196:197] op_sel_hi:[1,0,1]
	global_store_dwordx4 v[172:173], v[112:115], off
	global_store_dwordx4 v[172:173], v[116:119], off offset:256
	v_cvt_pk_bf16_f32 v104, v120, v121
	v_lshl_add_u64 v[112:113], s[28:29], 0, v[176:177]
	v_cvt_pk_bf16_f32 v105, v122, v123
	v_cvt_pk_bf16_f32 v106, v108, v109
	v_cvt_pk_bf16_f32 v107, v110, v111
	v_lshl_add_u64 v[112:113], v[112:113], 0, v[170:171]
	v_cvt_pk_bf16_f32 v146, v100, v101
	v_cvt_pk_bf16_f32 v147, v102, v103
	v_cvt_pk_bf16_f32 v148, v124, v125
	v_cvt_pk_bf16_f32 v149, v126, v127
	global_store_dwordx4 v[112:113], v[104:107], off
	global_store_dwordx4 v[112:113], v[146:149], off offset:256
	v_cvt_pk_bf16_f32 v194, v92, v93
	v_lshl_add_u64 v[104:105], s[28:29], 0, v[180:181]
	v_cvt_pk_bf16_f32 v195, v94, v95
	v_cvt_pk_bf16_f32 v196, v88, v89
	v_cvt_pk_bf16_f32 v197, v90, v91
	v_lshl_add_u64 v[104:105], v[104:105], 0, v[170:171]
	v_cvt_pk_bf16_f32 v214, v96, v97
	v_cvt_pk_bf16_f32 v215, v136, v137
	v_cvt_pk_bf16_f32 v216, v98, v99
	v_cvt_pk_bf16_f32 v217, v138, v139
	global_store_dwordx4 v[104:105], v[194:197], off
	global_store_dwordx4 v[104:105], v[214:217], off offset:256
	v_lshl_add_u64 v[104:105], s[28:29], 0, v[178:179]
	v_cvt_pk_bf16_f32 v222, v74, v75
	v_cvt_pk_bf16_f32 v223, v80, v81
	v_cvt_pk_bf16_f32 v224, v78, v79
	v_cvt_pk_bf16_f32 v225, v82, v83
	v_lshl_add_u64 v[104:105], v[104:105], 0, v[170:171]
	v_cvt_pk_bf16_f32 v230, v84, v85
	v_cvt_pk_bf16_f32 v231, v128, v129
	v_cvt_pk_bf16_f32 v232, v86, v87
	v_cvt_pk_bf16_f32 v233, v130, v131
	global_store_dwordx4 v[104:105], v[222:225], off
	global_store_dwordx4 v[104:105], v[230:233], off offset:256
	s_waitcnt vmcnt(8)
	v_lshlrev_b32_e32 v104, 16, v210
	v_and_b32_e32 v105, 0xffff0000, v210
	v_pk_fma_f32 v[60:61], v[60:61], 0.5, v[104:105] op_sel_hi:[1,0,1]
	v_lshlrev_b32_e32 v104, 16, v212
	v_and_b32_e32 v105, 0xffff0000, v212
	v_pk_fma_f32 v[56:57], v[56:57], 0.5, v[104:105] op_sel_hi:[1,0,1]
	v_lshlrev_b32_e32 v104, 16, v211
	v_and_b32_e32 v105, 0xffff0000, v211
	v_pk_fma_f32 v[62:63], v[62:63], 0.5, v[104:105] op_sel_hi:[1,0,1]
	v_lshlrev_b32_e32 v104, 16, v213
	v_and_b32_e32 v105, 0xffff0000, v213
	v_pk_fma_f32 v[58:59], v[58:59], 0.5, v[104:105] op_sel_hi:[1,0,1]
	v_lshlrev_b32_e32 v104, 16, v218
	v_and_b32_e32 v105, 0xffff0000, v218
	v_pk_fma_f32 v[52:53], v[52:53], 0.5, v[104:105] op_sel_hi:[1,0,1]
	v_lshlrev_b32_e32 v104, 16, v220
	v_and_b32_e32 v105, 0xffff0000, v220
	v_pk_fma_f32 v[104:105], v[44:45], 0.5, v[104:105] op_sel_hi:[1,0,1]
	v_lshlrev_b32_e32 v44, 16, v219
	v_and_b32_e32 v45, 0xffff0000, v219
	v_pk_fma_f32 v[54:55], v[54:55], 0.5, v[44:45] op_sel_hi:[1,0,1]
	v_lshlrev_b32_e32 v44, 16, v221
	v_and_b32_e32 v45, 0xffff0000, v221
	v_pk_fma_f32 v[106:107], v[46:47], 0.5, v[44:45] op_sel_hi:[1,0,1]
	v_lshlrev_b32_e32 v44, 16, v226
	v_and_b32_e32 v45, 0xffff0000, v226
	v_pk_fma_f32 v[44:45], v[48:49], 0.5, v[44:45] op_sel_hi:[1,0,1]
	v_lshlrev_b32_e32 v48, 16, v229
	v_and_b32_e32 v49, 0xffff0000, v229
	v_pk_fma_f32 v[42:43], v[42:43], 0.5, v[48:49] op_sel_hi:[1,0,1]
	v_lshlrev_b32_e32 v48, 16, v234
	v_and_b32_e32 v49, 0xffff0000, v234
	v_pk_fma_f32 v[36:37], v[36:37], 0.5, v[48:49] op_sel_hi:[1,0,1]
	v_lshlrev_b32_e32 v48, 16, v236
	v_and_b32_e32 v49, 0xffff0000, v236
	v_lshlrev_b32_e32 v46, 16, v228
	v_and_b32_e32 v47, 0xffff0000, v228
	v_pk_fma_f32 v[48:49], v[28:29], 0.5, v[48:49] op_sel_hi:[1,0,1]
	v_lshlrev_b32_e32 v28, 16, v235
	v_and_b32_e32 v29, 0xffff0000, v235
	v_pk_fma_f32 v[40:41], v[40:41], 0.5, v[46:47] op_sel_hi:[1,0,1]
	v_lshlrev_b32_e32 v46, 16, v227
	v_and_b32_e32 v47, 0xffff0000, v227
	v_pk_fma_f32 v[38:39], v[38:39], 0.5, v[28:29] op_sel_hi:[1,0,1]
	v_lshlrev_b32_e32 v28, 16, v237
	v_and_b32_e32 v29, 0xffff0000, v237
	v_pk_fma_f32 v[46:47], v[50:51], 0.5, v[46:47] op_sel_hi:[1,0,1]
	v_pk_fma_f32 v[50:51], v[30:31], 0.5, v[28:29] op_sel_hi:[1,0,1]
	v_lshlrev_b32_e32 v28, 16, v238
	v_and_b32_e32 v29, 0xffff0000, v238
	v_lshlrev_b32_e32 v180, 16, v64
	v_and_b32_e32 v181, 0xffff0000, v64
	v_pk_fma_f32 v[28:29], v[32:33], 0.5, v[28:29] op_sel_hi:[1,0,1]
	v_lshlrev_b32_e32 v32, 16, v241
	v_and_b32_e32 v33, 0xffff0000, v241
	v_pk_fma_f32 v[4:5], v[4:5], 0.5, v[180:181] op_sel_hi:[1,0,1]
	v_lshlrev_b32_e32 v180, 16, v66
	v_and_b32_e32 v181, 0xffff0000, v66
	v_pk_fma_f32 v[26:27], v[26:27], 0.5, v[32:33] op_sel_hi:[1,0,1]
	v_lshlrev_b32_e32 v32, 16, v242
	v_and_b32_e32 v33, 0xffff0000, v242
	v_pk_fma_f32 v[0:1], v[0:1], 0.5, v[180:181] op_sel_hi:[1,0,1]
	v_lshl_add_u64 v[180:181], s[28:29], 0, v[182:183]
	v_cvt_pk_bf16_f32 v112, v60, v61
	v_cvt_pk_bf16_f32 v113, v62, v63
	v_cvt_pk_bf16_f32 v114, v56, v57
	v_cvt_pk_bf16_f32 v115, v58, v59
	v_pk_fma_f32 v[20:21], v[20:21], 0.5, v[32:33] op_sel_hi:[1,0,1]
	v_lshlrev_b32_e32 v32, 16, v244
	v_and_b32_e32 v33, 0xffff0000, v244
	v_lshl_add_u64 v[180:181], v[180:181], 0, v[170:171]
	v_cvt_pk_bf16_f32 v116, v52, v53
	v_cvt_pk_bf16_f32 v117, v54, v55
	v_cvt_pk_bf16_f32 v118, v104, v105
	v_cvt_pk_bf16_f32 v119, v106, v107
	v_lshlrev_b32_e32 v30, 16, v240
	v_and_b32_e32 v31, 0xffff0000, v240
	v_pk_fma_f32 v[32:33], v[12:13], 0.5, v[32:33] op_sel_hi:[1,0,1]
	v_lshlrev_b32_e32 v12, 16, v243
	v_and_b32_e32 v13, 0xffff0000, v243
	global_store_dwordx4 v[180:181], v[112:115], off
	global_store_dwordx4 v[180:181], v[116:119], off offset:256
	v_cvt_pk_bf16_f32 v146, v44, v45
	v_lshl_add_u64 v[112:113], s[28:29], 0, v[132:133]
	v_cvt_pk_bf16_f32 v147, v46, v47
	v_cvt_pk_bf16_f32 v148, v40, v41
	v_cvt_pk_bf16_f32 v149, v42, v43
	v_pk_fma_f32 v[24:25], v[24:25], 0.5, v[30:31] op_sel_hi:[1,0,1]
	v_lshlrev_b32_e32 v30, 16, v239
	v_and_b32_e32 v31, 0xffff0000, v239
	v_pk_fma_f32 v[22:23], v[22:23], 0.5, v[12:13] op_sel_hi:[1,0,1]
	v_lshlrev_b32_e32 v12, 16, v245
	v_and_b32_e32 v13, 0xffff0000, v245
	v_lshl_add_u64 v[112:113], v[112:113], 0, v[170:171]
	v_cvt_pk_bf16_f32 v172, v36, v37
	v_cvt_pk_bf16_f32 v173, v38, v39
	v_cvt_pk_bf16_f32 v174, v48, v49
	v_cvt_pk_bf16_f32 v175, v50, v51
	v_pk_fma_f32 v[30:31], v[34:35], 0.5, v[30:31] op_sel_hi:[1,0,1]
	v_pk_fma_f32 v[34:35], v[14:15], 0.5, v[12:13] op_sel_hi:[1,0,1]
	v_lshlrev_b32_e32 v12, 16, v246
	v_and_b32_e32 v13, 0xffff0000, v246
	v_lshlrev_b32_e32 v14, 16, v248
	v_and_b32_e32 v15, 0xffff0000, v248
	global_store_dwordx4 v[112:113], v[146:149], off
	global_store_dwordx4 v[112:113], v[172:175], off offset:256
	v_lshl_add_u64 v[112:113], s[28:29], 0, v[134:135]
	v_cvt_pk_bf16_f32 v176, v28, v29
	v_cvt_pk_bf16_f32 v177, v30, v31
	v_cvt_pk_bf16_f32 v178, v24, v25
	v_cvt_pk_bf16_f32 v179, v26, v27
	v_pk_fma_f32 v[12:13], v[16:17], 0.5, v[12:13] op_sel_hi:[1,0,1]
	v_pk_fma_f32 v[8:9], v[8:9], 0.5, v[14:15] op_sel_hi:[1,0,1]
	v_lshlrev_b32_e32 v14, 16, v247
	v_and_b32_e32 v15, 0xffff0000, v247
	v_lshlrev_b32_e32 v16, 16, v249
	v_and_b32_e32 v17, 0xffff0000, v249
	v_lshlrev_b32_e32 v64, 16, v65
	v_and_b32_e32 v65, 0xffff0000, v65
	v_lshl_add_u64 v[112:113], v[112:113], 0, v[170:171]
	v_cvt_pk_bf16_f32 v194, v20, v21
	v_cvt_pk_bf16_f32 v195, v22, v23
	v_cvt_pk_bf16_f32 v196, v32, v33
	v_cvt_pk_bf16_f32 v197, v34, v35
	v_pk_fma_f32 v[14:15], v[18:19], 0.5, v[14:15] op_sel_hi:[1,0,1]
	v_pk_fma_f32 v[10:11], v[10:11], 0.5, v[16:17] op_sel_hi:[1,0,1]
	v_pk_fma_f32 v[6:7], v[6:7], 0.5, v[64:65] op_sel_hi:[1,0,1]
	v_lshlrev_b32_e32 v64, 16, v67
	v_and_b32_e32 v65, 0xffff0000, v67
	global_store_dwordx4 v[112:113], v[176:179], off
	global_store_dwordx4 v[112:113], v[194:197], off offset:256
	v_lshl_add_u64 v[112:113], s[28:29], 0, v[184:185]
	v_cvt_pk_bf16_f32 v16, v12, v13
	v_cvt_pk_bf16_f32 v17, v14, v15
	v_cvt_pk_bf16_f32 v18, v8, v9
	v_cvt_pk_bf16_f32 v19, v10, v11
	v_pk_fma_f32 v[2:3], v[2:3], 0.5, v[64:65] op_sel_hi:[1,0,1]
	v_lshl_add_u64 v[112:113], v[112:113], 0, v[170:171]
	v_cvt_pk_bf16_f32 v64, v4, v5
	v_cvt_pk_bf16_f32 v65, v6, v7
	v_cvt_pk_bf16_f32 v66, v0, v1
	v_cvt_pk_bf16_f32 v67, v2, v3
	global_store_dwordx4 v[112:113], v[16:19], off
	global_store_dwordx4 v[112:113], v[64:67], off offset:256
	s_lshl_b32 s10, s81, 2
	v_and_b32_e32 v17, 64, v188
	v_xor_b32_e32 v16, 16, v188
	v_add_u32_e32 v17, 64, v17
	v_cmp_lt_i32_e32 vcc, v16, v17
	v_xor_b32_e32 v18, 32, v188
	s_ashr_i32 s11, s10, 31
	v_cndmask_b32_e32 v16, v188, v16, vcc
	v_lshlrev_b32_e32 v16, 2, v16
	ds_bpermute_b32 v19, v16, v209
	v_cmp_lt_i32_e32 vcc, v18, v17
	s_lshl_b64 s[10:11], s[10:11], 2
	s_add_u32 s38, s73, s10
	v_cndmask_b32_e32 v17, v188, v18, vcc
	v_lshlrev_b32_e32 v17, 2, v17
	s_waitcnt lgkmcnt(0)
	v_add_f32_e32 v18, v209, v19
	ds_bpermute_b32 v19, v17, v18
	s_addc_u32 s39, s74, s11
	s_and_saveexec_b64 s[46:47], s[42:43]
	s_cbranch_execz .LBB0_34
	s_waitcnt lgkmcnt(0)
	v_add_f32_e32 v64, v18, v19
	v_lshlrev_b64 v[18:19], 6, v[168:169]
	v_lshl_add_u64 v[18:19], s[38:39], 0, v[18:19]
	global_store_dword v[18:19], v64, off

.LBB0_103:
	s_add_u32 s6, s54, 0xfffc0080
	s_addc_u32 s19, s55, -1
	s_add_i32 s23, 0, 0x10000
	v_add_u32_e32 v146, s23, v206
	ds_read_b128 v[128:131], v146
	ds_read_b128 v[132:135], v146 offset:1024
	ds_read_b128 v[136:139], v146 offset:2048
	ds_read_b128 v[146:149], v146 offset:3072
	s_cmp_eq_u32 s12, 12
	s_cselect_b32 s69, s47, s19
	s_cselect_b32 s68, s46, s6
	s_cselect_b32 s59, s49, s11
	s_cselect_b32 s58, s48, s10
	v_lshl_add_u64 v[192:193], s[54:55], 0, v[158:159]
	s_add_i32 m0, s72, 0xc000
	ds_read_b128 v[162:165], v208
	ds_read_b128 v[166:169], v208 offset:1024
	ds_read_b128 v[170:173], v208 offset:2048
	ds_read_b128 v[174:177], v208 offset:3072
	ds_read_b128 v[178:181], v208 offset:4096
	ds_read_b128 v[182:185], v208 offset:5120
	ds_read_b128 v[194:197], v208 offset:6144
	ds_read_b128 v[210:213], v208 offset:7168
	global_load_lds_dwordx4 v[192:193], off
	v_lshl_add_u64 v[192:193], s[54:55], 0, v[160:161]
	s_add_i32 m0, s72, 0xe000
	s_nop 0
	global_load_lds_dwordx4 v[192:193], off
	s_add_i32 s6, 0, 0x14000
	v_add_u32_e32 v192, s6, v206
	ds_read_b128 v[214:217], v192
	ds_read_b128 v[218:221], v192 offset:1024
	ds_read_b128 v[222:225], v192 offset:2048
	ds_read_b128 v[226:229], v192 offset:3072
	s_waitcnt vmcnt(8)
	s_waitcnt lgkmcnt(0)
	s_barrier
	v_mfma_f32_16x16x32_bf16 v[124:127], v[128:131], v[162:165], v[124:127]
	v_mfma_f32_16x16x32_bf16 v[120:123], v[136:139], v[162:165], v[120:123]
	v_mfma_f32_16x16x32_bf16 v[108:111], v[128:131], v[170:173], v[108:111]
	v_mfma_f32_16x16x32_bf16 v[104:107], v[136:139], v[170:173], v[104:107]
	v_mfma_f32_16x16x32_bf16 v[96:99], v[128:131], v[178:181], v[96:99]
	v_mfma_f32_16x16x32_bf16 v[88:91], v[136:139], v[178:181], v[88:91]
	v_mfma_f32_16x16x32_bf16 v[84:87], v[128:131], v[194:197], v[84:87]
	v_mfma_f32_16x16x32_bf16 v[80:83], v[136:139], v[194:197], v[80:83]
	v_mfma_f32_16x16x32_bf16 v[124:127], v[132:135], v[166:169], v[124:127]
	v_mfma_f32_16x16x32_bf16 v[120:123], v[146:149], v[166:169], v[120:123]
	v_mfma_f32_16x16x32_bf16 v[108:111], v[132:135], v[174:177], v[108:111]
	v_mfma_f32_16x16x32_bf16 v[104:107], v[146:149], v[174:177], v[104:107]
	v_mfma_f32_16x16x32_bf16 v[96:99], v[132:135], v[182:185], v[96:99]
	v_mfma_f32_16x16x32_bf16 v[88:91], v[146:149], v[182:185], v[88:91]
	v_mfma_f32_16x16x32_bf16 v[84:87], v[132:135], v[210:213], v[84:87]
	v_mfma_f32_16x16x32_bf16 v[80:83], v[146:149], v[210:213], v[80:83]
	v_mfma_f32_16x16x32_bf16 v[116:119], v[214:217], v[162:165], v[116:119]
	v_mfma_f32_16x16x32_bf16 v[112:115], v[222:225], v[162:165], v[112:115]
	v_mfma_f32_16x16x32_bf16 v[100:103], v[214:217], v[170:173], v[100:103]
	v_mfma_f32_16x16x32_bf16 v[92:95], v[222:225], v[170:173], v[92:95]
	v_mfma_f32_16x16x32_bf16 v[76:79], v[214:217], v[178:181], v[76:79]
	v_mfma_f32_16x16x32_bf16 v[72:75], v[222:225], v[178:181], v[72:75]
	v_mfma_f32_16x16x32_bf16 v[68:71], v[214:217], v[194:197], v[68:71]
	v_mfma_f32_16x16x32_bf16 v[64:67], v[222:225], v[194:197], v[64:67]
	v_mfma_f32_16x16x32_bf16 v[116:119], v[218:221], v[166:169], v[116:119]
	v_mfma_f32_16x16x32_bf16 v[112:115], v[226:229], v[166:169], v[112:115]
	v_mfma_f32_16x16x32_bf16 v[100:103], v[218:221], v[174:177], v[100:103]
	v_mfma_f32_16x16x32_bf16 v[92:95], v[226:229], v[174:177], v[92:95]
	v_mfma_f32_16x16x32_bf16 v[76:79], v[218:221], v[182:185], v[76:79]
	v_mfma_f32_16x16x32_bf16 v[72:75], v[226:229], v[182:185], v[72:75]
	v_mfma_f32_16x16x32_bf16 v[68:71], v[218:221], v[210:213], v[68:71]
	v_mfma_f32_16x16x32_bf16 v[64:67], v[226:229], v[210:213], v[64:67]
	s_barrier
	s_add_i32 s19, s23, s71
	v_lshl_add_u64 v[192:193], s[58:59], 0, v[140:141]
	s_mov_b32 m0, s19
	v_lshl_add_u64 v[230:231], s[58:59], 0, v[150:151]
	global_load_lds_dwordx4 v[192:193], off
	s_add_i32 m0, s19, 0x2000
	s_nop 0
	global_load_lds_dwordx4 v[230:231], off
	s_mov_b32 m0, s72
	v_lshl_add_u64 v[232:233], s[68:69], 0, v[154:155]
	ds_read_b128 v[162:165], v208 offset:16384
	ds_read_b128 v[166:169], v208 offset:17408
	ds_read_b128 v[170:173], v208 offset:18432
	ds_read_b128 v[174:177], v208 offset:19456
	ds_read_b128 v[178:181], v208 offset:20480
	ds_read_b128 v[182:185], v208 offset:21504
	ds_read_b128 v[194:197], v208 offset:22528
	ds_read_b128 v[210:213], v208 offset:23552
	global_load_lds_dwordx4 v[232:233], off
	v_lshl_add_u64 v[234:235], s[68:69], 0, v[152:153]
	s_mov_b32 m0, s73
	s_nop 0
	global_load_lds_dwordx4 v[234:235], off
	s_add_u32 s86, s58, 0x40000
	s_addc_u32 s87, s59, 0
	s_add_i32 s6, s6, s71
	v_lshl_add_u64 v[250:251], s[86:87], 0, v[140:141]
	s_mov_b32 m0, s6
	s_nop 0
	global_load_lds_dwordx4 v[250:251], off
	v_lshl_add_u64 v[250:251], s[86:87], 0, v[150:151]
	s_add_i32 m0, s6, 0x2000
	s_nop 0
	global_load_lds_dwordx4 v[250:251], off
	s_waitcnt vmcnt(8)
	s_waitcnt lgkmcnt(0)
	s_barrier
	v_mfma_f32_16x16x32_bf16 v[60:63], v[128:131], v[162:165], v[60:63]
	v_mfma_f32_16x16x32_bf16 v[56:59], v[136:139], v[162:165], v[56:59]
	v_mfma_f32_16x16x32_bf16 v[48:51], v[128:131], v[170:173], v[48:51]
	v_mfma_f32_16x16x32_bf16 v[40:43], v[136:139], v[170:173], v[40:43]
	v_mfma_f32_16x16x32_bf16 v[32:35], v[128:131], v[178:181], v[32:35]
	v_mfma_f32_16x16x32_bf16 v[24:27], v[136:139], v[178:181], v[24:27]
	v_mfma_f32_16x16x32_bf16 v[16:19], v[128:131], v[194:197], v[16:19]
	v_mfma_f32_16x16x32_bf16 v[8:11], v[136:139], v[194:197], v[8:11]
	v_mfma_f32_16x16x32_bf16 v[60:63], v[132:135], v[166:169], v[60:63]
	v_mfma_f32_16x16x32_bf16 v[56:59], v[146:149], v[166:169], v[56:59]
	v_mfma_f32_16x16x32_bf16 v[48:51], v[132:135], v[174:177], v[48:51]
	v_mfma_f32_16x16x32_bf16 v[40:43], v[146:149], v[174:177], v[40:43]
	v_mfma_f32_16x16x32_bf16 v[32:35], v[132:135], v[182:185], v[32:35]
	v_mfma_f32_16x16x32_bf16 v[24:27], v[146:149], v[182:185], v[24:27]
	v_mfma_f32_16x16x32_bf16 v[16:19], v[132:135], v[210:213], v[16:19]
	v_mfma_f32_16x16x32_bf16 v[8:11], v[146:149], v[210:213], v[8:11]
	v_mfma_f32_16x16x32_bf16 v[52:55], v[214:217], v[162:165], v[52:55]
	v_mfma_f32_16x16x32_bf16 v[44:47], v[222:225], v[162:165], v[44:47]
	v_mfma_f32_16x16x32_bf16 v[36:39], v[214:217], v[170:173], v[36:39]
	v_mfma_f32_16x16x32_bf16 v[28:31], v[222:225], v[170:173], v[28:31]
	v_mfma_f32_16x16x32_bf16 v[20:23], v[214:217], v[178:181], v[20:23]
	v_mfma_f32_16x16x32_bf16 v[12:15], v[222:225], v[178:181], v[12:15]
	v_mfma_f32_16x16x32_bf16 v[4:7], v[214:217], v[194:197], v[4:7]
	v_mfma_f32_16x16x32_bf16 v[0:3], v[222:225], v[194:197], v[0:3]
	v_mfma_f32_16x16x32_bf16 v[52:55], v[218:221], v[166:169], v[52:55]
	v_mfma_f32_16x16x32_bf16 v[44:47], v[226:229], v[166:169], v[44:47]
	v_mfma_f32_16x16x32_bf16 v[36:39], v[218:221], v[174:177], v[36:39]
	v_mfma_f32_16x16x32_bf16 v[28:31], v[226:229], v[174:177], v[28:31]
	v_mfma_f32_16x16x32_bf16 v[20:23], v[218:221], v[182:185], v[20:23]
	v_mfma_f32_16x16x32_bf16 v[12:15], v[226:229], v[182:185], v[12:15]
	v_mfma_f32_16x16x32_bf16 v[4:7], v[218:221], v[210:213], v[4:7]
	v_mfma_f32_16x16x32_bf16 v[0:3], v[226:229], v[210:213], v[0:3]
	s_barrier
	s_add_i32 s6, 0, 0x18000
	v_add_u32_e32 v146, s6, v206
	ds_read_b128 v[128:131], v146
	ds_read_b128 v[132:135], v146 offset:1024
	ds_read_b128 v[136:139], v146 offset:2048
	ds_read_b128 v[146:149], v146 offset:3072
	s_add_u32 s68, s68, 0x40000
	s_addc_u32 s69, s69, 0
	s_mov_b32 m0, s74
	v_lshl_add_u64 v[214:215], s[68:69], 0, v[154:155]
	ds_read_b128 v[162:165], v208 offset:32768
	ds_read_b128 v[166:169], v208 offset:33792
	ds_read_b128 v[170:173], v208 offset:34816
	ds_read_b128 v[174:177], v208 offset:35840
	ds_read_b128 v[178:181], v208 offset:36864
	ds_read_b128 v[182:185], v208 offset:37888
	ds_read_b128 v[194:197], v208 offset:38912
	ds_read_b128 v[210:213], v208 offset:39936
	global_load_lds_dwordx4 v[214:215], off
	v_lshl_add_u64 v[214:215], s[68:69], 0, v[152:153]
	s_mov_b32 m0, s75
	s_nop 0
	global_load_lds_dwordx4 v[214:215], off
	s_add_i32 s19, 0, 0x1c000
	v_add_u32_e32 v209, s19, v206
	ds_read_b128 v[214:217], v209
	ds_read_b128 v[218:221], v209 offset:1024
	ds_read_b128 v[222:225], v209 offset:2048
	ds_read_b128 v[226:229], v209 offset:3072
	s_waitcnt vmcnt(8)
	s_waitcnt lgkmcnt(0)
	s_barrier
	v_mfma_f32_16x16x32_bf16 v[124:127], v[128:131], v[162:165], v[124:127]
	v_mfma_f32_16x16x32_bf16 v[120:123], v[136:139], v[162:165], v[120:123]
	v_mfma_f32_16x16x32_bf16 v[108:111], v[128:131], v[170:173], v[108:111]
	v_mfma_f32_16x16x32_bf16 v[104:107], v[136:139], v[170:173], v[104:107]
	v_mfma_f32_16x16x32_bf16 v[96:99], v[128:131], v[178:181], v[96:99]
	v_mfma_f32_16x16x32_bf16 v[88:91], v[136:139], v[178:181], v[88:91]
	v_mfma_f32_16x16x32_bf16 v[84:87], v[128:131], v[194:197], v[84:87]
	v_mfma_f32_16x16x32_bf16 v[80:83], v[136:139], v[194:197], v[80:83]
	v_mfma_f32_16x16x32_bf16 v[124:127], v[132:135], v[166:169], v[124:127]
	v_mfma_f32_16x16x32_bf16 v[120:123], v[146:149], v[166:169], v[120:123]
	v_mfma_f32_16x16x32_bf16 v[108:111], v[132:135], v[174:177], v[108:111]
	v_mfma_f32_16x16x32_bf16 v[104:107], v[146:149], v[174:177], v[104:107]
	v_mfma_f32_16x16x32_bf16 v[96:99], v[132:135], v[182:185], v[96:99]
	v_mfma_f32_16x16x32_bf16 v[88:91], v[146:149], v[182:185], v[88:91]
	v_mfma_f32_16x16x32_bf16 v[84:87], v[132:135], v[210:213], v[84:87]
	v_mfma_f32_16x16x32_bf16 v[80:83], v[146:149], v[210:213], v[80:83]
	v_mfma_f32_16x16x32_bf16 v[116:119], v[214:217], v[162:165], v[116:119]
	v_mfma_f32_16x16x32_bf16 v[112:115], v[222:225], v[162:165], v[112:115]
	v_mfma_f32_16x16x32_bf16 v[100:103], v[214:217], v[170:173], v[100:103]
	v_mfma_f32_16x16x32_bf16 v[92:95], v[222:225], v[170:173], v[92:95]
	v_mfma_f32_16x16x32_bf16 v[76:79], v[214:217], v[178:181], v[76:79]
	v_mfma_f32_16x16x32_bf16 v[72:75], v[222:225], v[178:181], v[72:75]
	v_mfma_f32_16x16x32_bf16 v[68:71], v[214:217], v[194:197], v[68:71]
	v_mfma_f32_16x16x32_bf16 v[64:67], v[222:225], v[194:197], v[64:67]
	v_mfma_f32_16x16x32_bf16 v[116:119], v[218:221], v[166:169], v[116:119]
	v_mfma_f32_16x16x32_bf16 v[112:115], v[226:229], v[166:169], v[112:115]
	v_mfma_f32_16x16x32_bf16 v[100:103], v[218:221], v[174:177], v[100:103]
	v_mfma_f32_16x16x32_bf16 v[92:95], v[226:229], v[174:177], v[92:95]
	v_mfma_f32_16x16x32_bf16 v[76:79], v[218:221], v[182:185], v[76:79]
	v_mfma_f32_16x16x32_bf16 v[72:75], v[226:229], v[182:185], v[72:75]
	v_mfma_f32_16x16x32_bf16 v[68:71], v[218:221], v[210:213], v[68:71]
	v_mfma_f32_16x16x32_bf16 v[64:67], v[226:229], v[210:213], v[64:67]
	s_barrier
	s_add_i32 s6, s6, s71
	v_lshl_add_u64 v[192:193], v[192:193], 0, s[36:37]
	s_mov_b32 m0, s6
	s_nop 0
	global_load_lds_dwordx4 v[192:193], off
	v_lshl_add_u64 v[192:193], v[230:231], 0, s[36:37]
	s_add_i32 m0, s6, 0x2000
	s_nop 0
	global_load_lds_dwordx4 v[192:193], off
	s_mov_b32 m0, s80
	v_lshl_add_u64 v[192:193], v[232:233], 0, s[36:37]
	ds_read_b128 v[162:165], v208 offset:49152
	ds_read_b128 v[166:169], v208 offset:50176
	ds_read_b128 v[170:173], v208 offset:51200
	ds_read_b128 v[174:177], v208 offset:52224
	ds_read_b128 v[178:181], v208 offset:53248
	ds_read_b128 v[182:185], v208 offset:54272
	ds_read_b128 v[194:197], v208 offset:55296
	ds_read_b128 v[210:213], v208 offset:56320
	global_load_lds_dwordx4 v[192:193], off
	v_lshl_add_u64 v[192:193], v[234:235], 0, s[36:37]
	s_mov_b32 m0, s81
	s_nop 0
	global_load_lds_dwordx4 v[192:193], off
	s_add_u32 s58, s58, 0x40080
	s_addc_u32 s59, s59, 0
	s_add_i32 s6, s19, s71
	v_lshl_add_u64 v[250:251], s[58:59], 0, v[140:141]
	s_mov_b32 m0, s6
	s_nop 0
	global_load_lds_dwordx4 v[250:251], off
	v_lshl_add_u64 v[250:251], s[58:59], 0, v[150:151]
	s_add_i32 m0, s6, 0x2000
	s_nop 0
	global_load_lds_dwordx4 v[250:251], off
	s_waitcnt vmcnt(8)
	s_waitcnt lgkmcnt(0)
	s_barrier
	v_mfma_f32_16x16x32_bf16 v[60:63], v[128:131], v[162:165], v[60:63]
	v_mfma_f32_16x16x32_bf16 v[56:59], v[136:139], v[162:165], v[56:59]
	v_mfma_f32_16x16x32_bf16 v[48:51], v[128:131], v[170:173], v[48:51]
	v_mfma_f32_16x16x32_bf16 v[40:43], v[136:139], v[170:173], v[40:43]
	v_mfma_f32_16x16x32_bf16 v[32:35], v[128:131], v[178:181], v[32:35]
	v_mfma_f32_16x16x32_bf16 v[24:27], v[136:139], v[178:181], v[24:27]
	v_mfma_f32_16x16x32_bf16 v[16:19], v[128:131], v[194:197], v[16:19]
	v_mfma_f32_16x16x32_bf16 v[8:11], v[136:139], v[194:197], v[8:11]
	v_mfma_f32_16x16x32_bf16 v[60:63], v[132:135], v[166:169], v[60:63]
	v_mfma_f32_16x16x32_bf16 v[56:59], v[146:149], v[166:169], v[56:59]
	v_mfma_f32_16x16x32_bf16 v[48:51], v[132:135], v[174:177], v[48:51]
	v_mfma_f32_16x16x32_bf16 v[40:43], v[146:149], v[174:177], v[40:43]
	v_mfma_f32_16x16x32_bf16 v[32:35], v[132:135], v[182:185], v[32:35]
	v_mfma_f32_16x16x32_bf16 v[24:27], v[146:149], v[182:185], v[24:27]
	v_mfma_f32_16x16x32_bf16 v[16:19], v[132:135], v[210:213], v[16:19]
	v_mfma_f32_16x16x32_bf16 v[8:11], v[146:149], v[210:213], v[8:11]
	v_mfma_f32_16x16x32_bf16 v[52:55], v[214:217], v[162:165], v[52:55]
	v_mfma_f32_16x16x32_bf16 v[44:47], v[222:225], v[162:165], v[44:47]
	v_mfma_f32_16x16x32_bf16 v[36:39], v[214:217], v[170:173], v[36:39]
	v_mfma_f32_16x16x32_bf16 v[28:31], v[222:225], v[170:173], v[28:31]
	v_mfma_f32_16x16x32_bf16 v[20:23], v[214:217], v[178:181], v[20:23]
	v_mfma_f32_16x16x32_bf16 v[12:15], v[222:225], v[178:181], v[12:15]
	v_mfma_f32_16x16x32_bf16 v[4:7], v[214:217], v[194:197], v[4:7]
	v_mfma_f32_16x16x32_bf16 v[0:3], v[222:225], v[194:197], v[0:3]
	v_mfma_f32_16x16x32_bf16 v[52:55], v[218:221], v[166:169], v[52:55]
	v_mfma_f32_16x16x32_bf16 v[44:47], v[226:229], v[166:169], v[44:47]
	v_mfma_f32_16x16x32_bf16 v[36:39], v[218:221], v[174:177], v[36:39]
	v_mfma_f32_16x16x32_bf16 v[28:31], v[226:229], v[174:177], v[28:31]
	v_mfma_f32_16x16x32_bf16 v[20:23], v[218:221], v[182:185], v[20:23]
	v_mfma_f32_16x16x32_bf16 v[12:15], v[226:229], v[182:185], v[12:15]
	v_mfma_f32_16x16x32_bf16 v[4:7], v[218:221], v[210:213], v[4:7]
	v_mfma_f32_16x16x32_bf16 v[0:3], v[226:229], v[210:213], v[0:3]
	s_add_i32 s12, s12, 2
	s_add_u32 s54, s54, 0x100
	s_addc_u32 s55, s55, 0
	s_add_u32 s10, s10, 0x100
	s_addc_u32 s11, s11, 0
	s_cmp_gt_u32 s12, 13
	s_barrier
	s_cbranch_scc0 .LBB0_103
	s_mov_b32 s100, 1
	s_ashr_i32 s51, s50, 31
	s_ashr_i32 s53, s52, 31
	s_lshl_b64 s[10:11], s[50:51], 13
	s_lshl_b64 s[50:51], s[52:53], 8
	s_add_u32 s10, s50, s10
	v_lshl_or_b32 v128, s85, 8, v207
	s_addc_u32 s11, s51, s11
	v_ashrrev_i32_e32 v129, 31, v128
	v_lshl_add_u64 v[168:169], s[10:11], 0, v[156:157]
	v_lshlrev_b64 v[170:171], 1, v[128:129]
	v_lshl_add_u64 v[174:175], s[26:27], 0, v[170:171]
	v_lshlrev_b64 v[172:173], 11, v[168:169]
	v_or_b32_e32 v166, 16, v168
	v_mov_b32_e32 v167, v169
	v_lshl_add_u64 v[128:129], v[174:175], 0, v[172:173]
	v_lshlrev_b64 v[176:177], 11, v[166:167]
	global_load_dwordx4 v[146:149], v[128:129], off
	global_load_dwordx4 v[182:185], v[128:129], off offset:256
	v_lshl_add_u64 v[128:129], v[174:175], 0, v[176:177]
	global_load_dwordx4 v[194:197], v[128:129], off
	global_load_dwordx4 v[210:213], v[128:129], off offset:256
	v_or_b32_e32 v164, 32, v168
	v_mov_b32_e32 v165, v169
	v_or_b32_e32 v162, 48, v168
	v_mov_b32_e32 v163, v169
	v_lshlrev_b64 v[180:181], 11, v[164:165]
	v_lshlrev_b64 v[178:179], 11, v[162:163]
	v_lshl_add_u64 v[128:129], v[174:175], 0, v[180:181]
	v_lshl_add_u64 v[130:131], v[174:175], 0, v[178:179]
	global_load_dwordx4 v[214:217], v[128:129], off
	global_load_dwordx4 v[136:139], v[128:129], off offset:256
	global_load_dwordx4 v[132:135], v[130:131], off
	s_nop 0
	global_load_dwordx4 v[128:131], v[130:131], off offset:256
	s_mov_b64 s[10:11], 0x90
	v_lshl_add_u64 v[172:173], s[28:29], 0, v[172:173]
	v_lshl_add_u64 v[172:173], v[172:173], 0, v[170:171]
	s_waitcnt vmcnt(0)
	v_lshlrev_b32_e32 v192, 16, v146
	v_and_b32_e32 v193, 0xffff0000, v146
	v_lshlrev_b32_e32 v218, 16, v148
	v_and_b32_e32 v219, 0xffff0000, v148
	v_lshlrev_b32_e32 v146, 16, v147
	v_and_b32_e32 v147, 0xffff0000, v147
	v_lshlrev_b32_e32 v148, 16, v149
	v_and_b32_e32 v149, 0xffff0000, v149
	v_lshlrev_b32_e32 v220, 16, v182
	v_and_b32_e32 v221, 0xffff0000, v182
	v_lshlrev_b32_e32 v222, 16, v184
	v_and_b32_e32 v223, 0xffff0000, v184
	v_lshlrev_b32_e32 v182, 16, v183
	v_and_b32_e32 v183, 0xffff0000, v183
	v_lshlrev_b32_e32 v184, 16, v185
	v_and_b32_e32 v185, 0xffff0000, v185
	v_pk_add_f32 v[124:125], v[124:125], v[192:193]
	v_pk_add_f32 v[126:127], v[126:127], v[146:147]
	v_pk_add_f32 v[122:123], v[122:123], v[148:149]
	v_pk_add_f32 v[116:117], v[116:117], v[220:221]
	v_pk_add_f32 v[146:147], v[112:113], v[222:223]
	v_pk_add_f32 v[118:119], v[118:119], v[182:183]
	v_pk_add_f32 v[148:149], v[114:115], v[184:185]
	v_lshlrev_b32_e32 v182, 16, v194
	v_and_b32_e32 v183, 0xffff0000, v194
	v_lshlrev_b32_e32 v184, 16, v196
	v_and_b32_e32 v185, 0xffff0000, v196
	v_lshlrev_b32_e32 v192, 16, v195
	v_and_b32_e32 v193, 0xffff0000, v195
	v_lshlrev_b32_e32 v194, 16, v197
	v_and_b32_e32 v195, 0xffff0000, v197
	v_pk_mul_f32 v[196:197], v[124:125], v[124:125]
	v_pk_add_f32 v[120:121], v[120:121], v[218:219]
	v_pk_mul_f32 v[218:219], v[126:127], v[126:127]
	v_cvt_pk_bf16_f32 v112, v124, v125
	v_cvt_pk_bf16_f32 v113, v126, v127
	v_pk_mul_f32 v[124:125], v[116:117], v[116:117]
	v_pk_mul_f32 v[126:127], v[118:119], v[118:119]
	v_pk_mul_f32 v[224:225], v[146:147], v[146:147]
	v_cvt_pk_bf16_f32 v116, v116, v117
	v_cvt_pk_bf16_f32 v117, v118, v119
	v_cvt_pk_bf16_f32 v118, v146, v147
	v_add_f32_e32 v146, v196, v197
	v_add_f32_e32 v146, v218, v146
	v_pk_mul_f32 v[220:221], v[120:121], v[120:121]
	v_add_f32_e32 v146, v219, v146
	v_add_f32_e32 v146, v220, v146
	v_pk_mul_f32 v[222:223], v[122:123], v[122:123]
	v_add_f32_e32 v146, v221, v146
	v_add_f32_e32 v146, v222, v146
	v_add_f32_e32 v146, v223, v146
	v_add_f32_e32 v124, v124, v146
	v_add_f32_e32 v124, v125, v124
	v_add_f32_e32 v124, v126, v124
	v_add_f32_e32 v124, v127, v124
	v_add_f32_e32 v124, v224, v124
	v_pk_mul_f32 v[226:227], v[148:149], v[148:149]
	v_add_f32_e32 v124, v225, v124
	v_add_f32_e32 v124, v226, v124
	v_add_f32_e32 v209, v227, v124
	v_lshlrev_b32_e32 v124, 16, v210
	v_and_b32_e32 v125, 0xffff0000, v210
	v_pk_add_f32 v[100:101], v[100:101], v[124:125]
	v_lshlrev_b32_e32 v124, 16, v212
	v_and_b32_e32 v125, 0xffff0000, v212
	v_pk_add_f32 v[124:125], v[92:93], v[124:125]
	v_lshlrev_b32_e32 v92, 16, v211
	v_and_b32_e32 v93, 0xffff0000, v211
	v_pk_add_f32 v[102:103], v[102:103], v[92:93]
	v_lshlrev_b32_e32 v92, 16, v213
	v_and_b32_e32 v93, 0xffff0000, v213
	v_pk_add_f32 v[126:127], v[94:95], v[92:93]
	v_lshlrev_b32_e32 v92, 16, v214
	v_and_b32_e32 v93, 0xffff0000, v214
	v_pk_add_f32 v[92:93], v[96:97], v[92:93]
	v_lshlrev_b32_e32 v96, 16, v217
	v_and_b32_e32 v97, 0xffff0000, v217
	v_lshlrev_b32_e32 v94, 16, v216
	v_and_b32_e32 v95, 0xffff0000, v216
	v_pk_add_f32 v[90:91], v[90:91], v[96:97]
	v_lshlrev_b32_e32 v96, 16, v136
	v_and_b32_e32 v97, 0xffff0000, v136
	v_pk_add_f32 v[88:89], v[88:89], v[94:95]
	v_lshlrev_b32_e32 v94, 16, v215
	v_and_b32_e32 v95, 0xffff0000, v215
	v_pk_add_f32 v[96:97], v[76:77], v[96:97]
	v_lshl_add_u64 v[76:77], v[168:169], 0, s[36:37]
	v_cvt_pk_bf16_f32 v114, v120, v121
	v_pk_add_f32 v[120:121], v[108:109], v[182:183]
	v_pk_add_f32 v[94:95], v[98:99], v[94:95]
	v_lshlrev_b64 v[182:183], 11, v[76:77]
	v_lshlrev_b32_e32 v98, 16, v138
	v_and_b32_e32 v99, 0xffff0000, v138
	v_pk_add_f32 v[108:109], v[104:105], v[184:185]
	v_lshl_add_u64 v[184:185], v[174:175], 0, v[182:183]
	v_pk_add_f32 v[98:99], v[72:73], v[98:99]
	v_lshlrev_b32_e32 v72, 16, v137
	v_and_b32_e32 v73, 0xffff0000, v137
	global_load_dwordx4 v[210:213], v[184:185], off
	global_load_dwordx4 v[218:221], v[184:185], off offset:256
	v_pk_add_f32 v[136:137], v[78:79], v[72:73]
	v_lshlrev_b32_e32 v72, 16, v139
	v_and_b32_e32 v73, 0xffff0000, v139
	v_pk_add_f32 v[138:139], v[74:75], v[72:73]
	v_lshlrev_b32_e32 v72, 16, v132
	v_and_b32_e32 v73, 0xffff0000, v132
	v_pk_add_f32 v[74:75], v[84:85], v[72:73]
	v_lshlrev_b32_e32 v72, 16, v134
	v_and_b32_e32 v73, 0xffff0000, v134
	v_pk_add_f32 v[78:79], v[80:81], v[72:73]
	v_lshlrev_b32_e32 v72, 16, v133
	v_and_b32_e32 v73, 0xffff0000, v133
	v_pk_add_f32 v[80:81], v[86:87], v[72:73]
	v_lshlrev_b32_e32 v72, 16, v135
	v_and_b32_e32 v73, 0xffff0000, v135
	v_pk_add_f32 v[82:83], v[82:83], v[72:73]
	v_lshl_add_u64 v[72:73], v[168:169], 0, s[10:11]
	v_lshlrev_b64 v[132:133], 11, v[72:73]
	v_lshl_add_u64 v[134:135], v[174:175], 0, v[132:133]
	v_lshlrev_b32_e32 v84, 16, v128
	v_and_b32_e32 v85, 0xffff0000, v128
	global_load_dwordx4 v[226:229], v[134:135], off
	global_load_dwordx4 v[234:237], v[134:135], off offset:256
	v_pk_add_f32 v[84:85], v[68:69], v[84:85]
	v_lshlrev_b32_e32 v68, 16, v130
	v_and_b32_e32 v69, 0xffff0000, v130
	v_pk_add_f32 v[86:87], v[64:65], v[68:69]
	v_lshlrev_b32_e32 v64, 16, v129
	v_and_b32_e32 v65, 0xffff0000, v129
	s_mov_b64 s[10:11], 0xa0
	v_pk_add_f32 v[128:129], v[70:71], v[64:65]
	v_lshl_add_u64 v[70:71], v[168:169], 0, s[10:11]
	s_mov_b64 s[10:11], 0xb0
	v_lshlrev_b32_e32 v64, 16, v131
	v_and_b32_e32 v65, 0xffff0000, v131
	v_lshlrev_b64 v[134:135], 11, v[70:71]
	v_lshl_add_u64 v[68:69], v[168:169], 0, s[10:11]
	v_pk_add_f32 v[130:131], v[66:67], v[64:65]
	v_lshl_add_u64 v[64:65], v[174:175], 0, v[134:135]
	v_lshlrev_b64 v[184:185], 11, v[68:69]
	global_load_dwordx4 v[238:241], v[64:65], off
	global_load_dwordx4 v[242:245], v[64:65], off offset:256
	v_lshl_add_u64 v[64:65], v[174:175], 0, v[184:185]
	global_load_dwordx4 v[246:249], v[64:65], off
	s_nop 0
	global_load_dwordx4 v[64:67], v[64:65], off offset:256
	v_cvt_pk_bf16_f32 v115, v122, v123
	v_cvt_pk_bf16_f32 v119, v148, v149
	v_pk_add_f32 v[110:111], v[110:111], v[192:193]
	v_pk_add_f32 v[122:123], v[106:107], v[194:195]
	global_store_dwordx4 v[172:173], v[112:115], off
	global_store_dwordx4 v[172:173], v[116:119], off offset:256
	v_cvt_pk_bf16_f32 v104, v120, v121
	v_lshl_add_u64 v[112:113], s[28:29], 0, v[176:177]
	v_cvt_pk_bf16_f32 v105, v110, v111
	v_cvt_pk_bf16_f32 v106, v108, v109
	v_cvt_pk_bf16_f32 v107, v122, v123
	v_lshl_add_u64 v[112:113], v[112:113], 0, v[170:171]
	v_cvt_pk_bf16_f32 v146, v100, v101
	v_cvt_pk_bf16_f32 v147, v102, v103
	v_cvt_pk_bf16_f32 v148, v124, v125
	v_cvt_pk_bf16_f32 v149, v126, v127
	global_store_dwordx4 v[112:113], v[104:107], off
	global_store_dwordx4 v[112:113], v[146:149], off offset:256
	v_cvt_pk_bf16_f32 v194, v92, v93
	v_lshl_add_u64 v[104:105], s[28:29], 0, v[180:181]
	v_cvt_pk_bf16_f32 v195, v94, v95
	v_cvt_pk_bf16_f32 v196, v88, v89
	v_cvt_pk_bf16_f32 v197, v90, v91
	v_lshl_add_u64 v[104:105], v[104:105], 0, v[170:171]
	v_cvt_pk_bf16_f32 v214, v96, v97
	v_cvt_pk_bf16_f32 v215, v136, v137
	v_cvt_pk_bf16_f32 v216, v98, v99
	v_cvt_pk_bf16_f32 v217, v138, v139
	global_store_dwordx4 v[104:105], v[194:197], off
	global_store_dwordx4 v[104:105], v[214:217], off offset:256
	v_lshl_add_u64 v[104:105], s[28:29], 0, v[178:179]
	v_cvt_pk_bf16_f32 v222, v74, v75
	v_cvt_pk_bf16_f32 v223, v80, v81
	v_cvt_pk_bf16_f32 v224, v78, v79
	v_cvt_pk_bf16_f32 v225, v82, v83
	v_lshl_add_u64 v[104:105], v[104:105], 0, v[170:171]
	v_cvt_pk_bf16_f32 v230, v84, v85
	v_cvt_pk_bf16_f32 v231, v128, v129
	v_cvt_pk_bf16_f32 v232, v86, v87
	v_cvt_pk_bf16_f32 v233, v130, v131
	global_store_dwordx4 v[104:105], v[222:225], off
	global_store_dwordx4 v[104:105], v[230:233], off offset:256
	s_waitcnt vmcnt(8)
	v_lshlrev_b32_e32 v104, 16, v210
	v_and_b32_e32 v105, 0xffff0000, v210
	v_pk_add_f32 v[60:61], v[60:61], v[104:105]
	v_lshlrev_b32_e32 v104, 16, v212
	v_and_b32_e32 v105, 0xffff0000, v212
	v_pk_add_f32 v[56:57], v[56:57], v[104:105]
	v_lshlrev_b32_e32 v104, 16, v211
	v_and_b32_e32 v105, 0xffff0000, v211
	v_pk_add_f32 v[62:63], v[62:63], v[104:105]
	v_lshlrev_b32_e32 v104, 16, v213
	v_and_b32_e32 v105, 0xffff0000, v213
	v_pk_add_f32 v[58:59], v[58:59], v[104:105]
	v_lshlrev_b32_e32 v104, 16, v218
	v_and_b32_e32 v105, 0xffff0000, v218
	v_pk_add_f32 v[52:53], v[52:53], v[104:105]
	v_lshlrev_b32_e32 v104, 16, v220
	v_and_b32_e32 v105, 0xffff0000, v220
	v_pk_add_f32 v[104:105], v[44:45], v[104:105]
	v_lshlrev_b32_e32 v44, 16, v219
	v_and_b32_e32 v45, 0xffff0000, v219
	v_pk_add_f32 v[54:55], v[54:55], v[44:45]
	v_lshlrev_b32_e32 v44, 16, v221
	v_and_b32_e32 v45, 0xffff0000, v221
	v_pk_add_f32 v[106:107], v[46:47], v[44:45]
	v_lshlrev_b32_e32 v44, 16, v226
	v_and_b32_e32 v45, 0xffff0000, v226
	v_pk_add_f32 v[44:45], v[48:49], v[44:45]
	v_lshlrev_b32_e32 v48, 16, v229
	v_and_b32_e32 v49, 0xffff0000, v229
	v_pk_add_f32 v[42:43], v[42:43], v[48:49]
	v_lshlrev_b32_e32 v48, 16, v234
	v_and_b32_e32 v49, 0xffff0000, v234
	v_pk_add_f32 v[36:37], v[36:37], v[48:49]
	v_lshlrev_b32_e32 v48, 16, v236
	v_and_b32_e32 v49, 0xffff0000, v236
	v_lshlrev_b32_e32 v46, 16, v228
	v_and_b32_e32 v47, 0xffff0000, v228
	v_pk_add_f32 v[48:49], v[28:29], v[48:49]
	v_lshlrev_b32_e32 v28, 16, v235
	v_and_b32_e32 v29, 0xffff0000, v235
	v_pk_add_f32 v[40:41], v[40:41], v[46:47]
	v_lshlrev_b32_e32 v46, 16, v227
	v_and_b32_e32 v47, 0xffff0000, v227
	v_pk_add_f32 v[38:39], v[38:39], v[28:29]
	v_lshlrev_b32_e32 v28, 16, v237
	v_and_b32_e32 v29, 0xffff0000, v237
	v_pk_add_f32 v[46:47], v[50:51], v[46:47]
	v_pk_add_f32 v[50:51], v[30:31], v[28:29]
	v_lshlrev_b32_e32 v28, 16, v238
	v_and_b32_e32 v29, 0xffff0000, v238
	v_lshlrev_b32_e32 v180, 16, v64
	v_and_b32_e32 v181, 0xffff0000, v64
	v_pk_add_f32 v[28:29], v[32:33], v[28:29]
	v_lshlrev_b32_e32 v32, 16, v241
	v_and_b32_e32 v33, 0xffff0000, v241
	v_pk_add_f32 v[4:5], v[4:5], v[180:181]
	v_lshlrev_b32_e32 v180, 16, v66
	v_and_b32_e32 v181, 0xffff0000, v66
	v_pk_add_f32 v[26:27], v[26:27], v[32:33]
	v_lshlrev_b32_e32 v32, 16, v242
	v_and_b32_e32 v33, 0xffff0000, v242
	v_pk_add_f32 v[0:1], v[0:1], v[180:181]
	v_lshl_add_u64 v[180:181], s[28:29], 0, v[182:183]
	v_cvt_pk_bf16_f32 v112, v60, v61
	v_cvt_pk_bf16_f32 v113, v62, v63
	v_cvt_pk_bf16_f32 v114, v56, v57
	v_cvt_pk_bf16_f32 v115, v58, v59
	v_pk_add_f32 v[20:21], v[20:21], v[32:33]
	v_lshlrev_b32_e32 v32, 16, v244
	v_and_b32_e32 v33, 0xffff0000, v244
	v_lshl_add_u64 v[180:181], v[180:181], 0, v[170:171]
	v_cvt_pk_bf16_f32 v116, v52, v53
	v_cvt_pk_bf16_f32 v117, v54, v55
	v_cvt_pk_bf16_f32 v118, v104, v105
	v_cvt_pk_bf16_f32 v119, v106, v107
	v_lshlrev_b32_e32 v30, 16, v240
	v_and_b32_e32 v31, 0xffff0000, v240
	v_pk_add_f32 v[32:33], v[12:13], v[32:33]
	v_lshlrev_b32_e32 v12, 16, v243
	v_and_b32_e32 v13, 0xffff0000, v243
	global_store_dwordx4 v[180:181], v[112:115], off
	global_store_dwordx4 v[180:181], v[116:119], off offset:256
	v_cvt_pk_bf16_f32 v146, v44, v45
	v_lshl_add_u64 v[112:113], s[28:29], 0, v[132:133]
	v_cvt_pk_bf16_f32 v147, v46, v47
	v_cvt_pk_bf16_f32 v148, v40, v41
	v_cvt_pk_bf16_f32 v149, v42, v43
	v_pk_add_f32 v[24:25], v[24:25], v[30:31]
	v_lshlrev_b32_e32 v30, 16, v239
	v_and_b32_e32 v31, 0xffff0000, v239
	v_pk_add_f32 v[22:23], v[22:23], v[12:13]
	v_lshlrev_b32_e32 v12, 16, v245
	v_and_b32_e32 v13, 0xffff0000, v245
	v_lshl_add_u64 v[112:113], v[112:113], 0, v[170:171]
	v_cvt_pk_bf16_f32 v172, v36, v37
	v_cvt_pk_bf16_f32 v173, v38, v39
	v_cvt_pk_bf16_f32 v174, v48, v49
	v_cvt_pk_bf16_f32 v175, v50, v51
	v_pk_add_f32 v[30:31], v[34:35], v[30:31]
	v_pk_add_f32 v[34:35], v[14:15], v[12:13]
	v_lshlrev_b32_e32 v12, 16, v246
	v_and_b32_e32 v13, 0xffff0000, v246
	v_lshlrev_b32_e32 v14, 16, v248
	v_and_b32_e32 v15, 0xffff0000, v248
	global_store_dwordx4 v[112:113], v[146:149], off
	global_store_dwordx4 v[112:113], v[172:175], off offset:256
	v_lshl_add_u64 v[112:113], s[28:29], 0, v[134:135]
	v_cvt_pk_bf16_f32 v176, v28, v29
	v_cvt_pk_bf16_f32 v177, v30, v31
	v_cvt_pk_bf16_f32 v178, v24, v25
	v_cvt_pk_bf16_f32 v179, v26, v27
	v_pk_add_f32 v[12:13], v[16:17], v[12:13]
	v_pk_add_f32 v[8:9], v[8:9], v[14:15]
	v_lshlrev_b32_e32 v14, 16, v247
	v_and_b32_e32 v15, 0xffff0000, v247
	v_lshlrev_b32_e32 v16, 16, v249
	v_and_b32_e32 v17, 0xffff0000, v249
	v_lshlrev_b32_e32 v64, 16, v65
	v_and_b32_e32 v65, 0xffff0000, v65
	v_lshl_add_u64 v[112:113], v[112:113], 0, v[170:171]
	v_cvt_pk_bf16_f32 v194, v20, v21
	v_cvt_pk_bf16_f32 v195, v22, v23
	v_cvt_pk_bf16_f32 v196, v32, v33
	v_cvt_pk_bf16_f32 v197, v34, v35
	v_pk_add_f32 v[14:15], v[18:19], v[14:15]
	v_pk_add_f32 v[10:11], v[10:11], v[16:17]
	v_pk_add_f32 v[6:7], v[6:7], v[64:65]
	v_lshlrev_b32_e32 v64, 16, v67
	v_and_b32_e32 v65, 0xffff0000, v67
	global_store_dwordx4 v[112:113], v[176:179], off
	global_store_dwordx4 v[112:113], v[194:197], off offset:256
	v_lshl_add_u64 v[112:113], s[28:29], 0, v[184:185]
	v_cvt_pk_bf16_f32 v16, v12, v13
	v_cvt_pk_bf16_f32 v17, v14, v15
	v_cvt_pk_bf16_f32 v18, v8, v9
	v_cvt_pk_bf16_f32 v19, v10, v11
	v_pk_add_f32 v[2:3], v[2:3], v[64:65]
	v_lshl_add_u64 v[112:113], v[112:113], 0, v[170:171]
	v_cvt_pk_bf16_f32 v64, v4, v5
	v_cvt_pk_bf16_f32 v65, v6, v7
	v_cvt_pk_bf16_f32 v66, v0, v1
	v_cvt_pk_bf16_f32 v67, v2, v3
	global_store_dwordx4 v[112:113], v[16:19], off
	global_store_dwordx4 v[112:113], v[64:67], off offset:256
	s_lshl_b32 s10, s85, 2
	v_and_b32_e32 v17, 64, v188
	v_xor_b32_e32 v16, 16, v188
	v_add_u32_e32 v17, 64, v17
	v_cmp_lt_i32_e32 vcc, v16, v17
	v_xor_b32_e32 v18, 32, v188
	s_ashr_i32 s11, s10, 31
	v_cndmask_b32_e32 v16, v188, v16, vcc
	v_lshlrev_b32_e32 v16, 2, v16
	ds_bpermute_b32 v19, v16, v209
	v_cmp_lt_i32_e32 vcc, v18, v17
	s_lshl_b64 s[10:11], s[10:11], 2
	s_add_u32 s50, s83, s10
	v_cndmask_b32_e32 v17, v188, v18, vcc
	v_lshlrev_b32_e32 v17, 2, v17
	s_waitcnt lgkmcnt(0)
	v_add_f32_e32 v18, v209, v19
	ds_bpermute_b32 v19, v17, v18
	s_addc_u32 s51, s84, s11
	s_and_saveexec_b64 s[52:53], s[42:43]
	s_cbranch_execz .LBB0_106
	s_waitcnt lgkmcnt(0)
	v_add_f32_e32 v64, v18, v19
	v_lshlrev_b64 v[18:19], 6, v[168:169]
	v_lshl_add_u64 v[18:19], s[50:51], 0, v[18:19]
	global_store_dword v[18:19], v64, off

.LBB0_248:
	s_add_u32 s6, s52, 0xfffc0080
	s_addc_u32 s19, s53, -1
	s_add_i32 s23, 0, 0x10000
	v_add_u32_e32 v146, s23, v206
	ds_read_b128 v[128:131], v146
	ds_read_b128 v[132:135], v146 offset:1024
	ds_read_b128 v[136:139], v146 offset:2048
	ds_read_b128 v[146:149], v146 offset:3072
	s_cmp_eq_u32 s82, 12
	s_cselect_b32 s59, s10, s19
	s_cselect_b32 s58, s11, s6
	s_cselect_b32 s55, s12, s51
	s_cselect_b32 s54, s35, s39
	v_lshl_add_u64 v[214:215], s[52:53], 0, v[158:159]
	s_add_i32 m0, s68, 0xc000
	ds_read_b128 v[162:165], v208
	ds_read_b128 v[166:169], v208 offset:1024
	ds_read_b128 v[170:173], v208 offset:2048
	ds_read_b128 v[174:177], v208 offset:3072
	ds_read_b128 v[178:181], v208 offset:4096
	ds_read_b128 v[182:185], v208 offset:5120
	ds_read_b128 v[194:197], v208 offset:6144
	ds_read_b128 v[210:213], v208 offset:7168
	global_load_lds_dwordx4 v[214:215], off
	v_lshl_add_u64 v[214:215], s[52:53], 0, v[160:161]
	s_add_i32 m0, s68, 0xe000
	s_nop 0
	global_load_lds_dwordx4 v[214:215], off
	s_add_i32 s6, 0, 0x14000
	v_add_u32_e32 v192, s6, v206
	ds_read_b128 v[214:217], v192
	ds_read_b128 v[218:221], v192 offset:1024
	ds_read_b128 v[222:225], v192 offset:2048
	ds_read_b128 v[226:229], v192 offset:3072
	s_waitcnt vmcnt(8)
	s_waitcnt lgkmcnt(0)
	s_barrier
	v_mfma_f32_16x16x32_bf16 v[124:127], v[128:131], v[162:165], v[124:127]
	v_mfma_f32_16x16x32_bf16 v[120:123], v[136:139], v[162:165], v[120:123]
	v_mfma_f32_16x16x32_bf16 v[108:111], v[128:131], v[170:173], v[108:111]
	v_mfma_f32_16x16x32_bf16 v[104:107], v[136:139], v[170:173], v[104:107]
	v_mfma_f32_16x16x32_bf16 v[96:99], v[128:131], v[178:181], v[96:99]
	v_mfma_f32_16x16x32_bf16 v[88:91], v[136:139], v[178:181], v[88:91]
	v_mfma_f32_16x16x32_bf16 v[84:87], v[128:131], v[194:197], v[84:87]
	v_mfma_f32_16x16x32_bf16 v[80:83], v[136:139], v[194:197], v[80:83]
	v_mfma_f32_16x16x32_bf16 v[124:127], v[132:135], v[166:169], v[124:127]
	v_mfma_f32_16x16x32_bf16 v[120:123], v[146:149], v[166:169], v[120:123]
	v_mfma_f32_16x16x32_bf16 v[108:111], v[132:135], v[174:177], v[108:111]
	v_mfma_f32_16x16x32_bf16 v[104:107], v[146:149], v[174:177], v[104:107]
	v_mfma_f32_16x16x32_bf16 v[96:99], v[132:135], v[182:185], v[96:99]
	v_mfma_f32_16x16x32_bf16 v[88:91], v[146:149], v[182:185], v[88:91]
	v_mfma_f32_16x16x32_bf16 v[84:87], v[132:135], v[210:213], v[84:87]
	v_mfma_f32_16x16x32_bf16 v[80:83], v[146:149], v[210:213], v[80:83]
	v_mfma_f32_16x16x32_bf16 v[116:119], v[214:217], v[162:165], v[116:119]
	v_mfma_f32_16x16x32_bf16 v[112:115], v[222:225], v[162:165], v[112:115]
	v_mfma_f32_16x16x32_bf16 v[100:103], v[214:217], v[170:173], v[100:103]
	v_mfma_f32_16x16x32_bf16 v[92:95], v[222:225], v[170:173], v[92:95]
	v_mfma_f32_16x16x32_bf16 v[76:79], v[214:217], v[178:181], v[76:79]
	v_mfma_f32_16x16x32_bf16 v[72:75], v[222:225], v[178:181], v[72:75]
	v_mfma_f32_16x16x32_bf16 v[68:71], v[214:217], v[194:197], v[68:71]
	v_mfma_f32_16x16x32_bf16 v[64:67], v[222:225], v[194:197], v[64:67]
	v_mfma_f32_16x16x32_bf16 v[116:119], v[218:221], v[166:169], v[116:119]
	v_mfma_f32_16x16x32_bf16 v[112:115], v[226:229], v[166:169], v[112:115]
	v_mfma_f32_16x16x32_bf16 v[100:103], v[218:221], v[174:177], v[100:103]
	v_mfma_f32_16x16x32_bf16 v[92:95], v[226:229], v[174:177], v[92:95]
	v_mfma_f32_16x16x32_bf16 v[76:79], v[218:221], v[182:185], v[76:79]
	v_mfma_f32_16x16x32_bf16 v[72:75], v[226:229], v[182:185], v[72:75]
	v_mfma_f32_16x16x32_bf16 v[68:71], v[218:221], v[210:213], v[68:71]
	v_mfma_f32_16x16x32_bf16 v[64:67], v[226:229], v[210:213], v[64:67]
	s_barrier
	s_add_i32 s19, s23, s57
	v_lshl_add_u64 v[230:231], s[54:55], 0, v[140:141]
	s_mov_b32 m0, s19
	s_nop 0
	global_load_lds_dwordx4 v[230:231], off
	v_lshl_add_u64 v[232:233], s[54:55], 0, v[150:151]
	s_add_i32 m0, s19, 0x2000
	s_nop 0
	global_load_lds_dwordx4 v[232:233], off
	s_mov_b32 m0, s68
	v_lshl_add_u64 v[234:235], s[58:59], 0, v[154:155]
	ds_read_b128 v[162:165], v208 offset:16384
	ds_read_b128 v[166:169], v208 offset:17408
	ds_read_b128 v[170:173], v208 offset:18432
	ds_read_b128 v[174:177], v208 offset:19456
	ds_read_b128 v[178:181], v208 offset:20480
	ds_read_b128 v[182:185], v208 offset:21504
	ds_read_b128 v[194:197], v208 offset:22528
	ds_read_b128 v[210:213], v208 offset:23552
	global_load_lds_dwordx4 v[234:235], off
	v_lshl_add_u64 v[236:237], s[58:59], 0, v[152:153]
	s_mov_b32 m0, s69
	s_nop 0
	global_load_lds_dwordx4 v[236:237], off
	s_add_u32 s84, s54, 0x40000
	s_addc_u32 s85, s55, 0
	s_add_i32 s6, s6, s57
	v_lshl_add_u64 v[250:251], s[84:85], 0, v[140:141]
	s_mov_b32 m0, s6
	s_nop 0
	global_load_lds_dwordx4 v[250:251], off
	v_lshl_add_u64 v[250:251], s[84:85], 0, v[150:151]
	s_add_i32 m0, s6, 0x2000
	s_nop 0
	global_load_lds_dwordx4 v[250:251], off
	s_waitcnt vmcnt(8)
	s_waitcnt lgkmcnt(0)
	s_barrier
	v_mfma_f32_16x16x32_bf16 v[60:63], v[128:131], v[162:165], v[60:63]
	v_mfma_f32_16x16x32_bf16 v[56:59], v[136:139], v[162:165], v[56:59]
	v_mfma_f32_16x16x32_bf16 v[48:51], v[128:131], v[170:173], v[48:51]
	v_mfma_f32_16x16x32_bf16 v[40:43], v[136:139], v[170:173], v[40:43]
	v_mfma_f32_16x16x32_bf16 v[32:35], v[128:131], v[178:181], v[32:35]
	v_mfma_f32_16x16x32_bf16 v[24:27], v[136:139], v[178:181], v[24:27]
	v_mfma_f32_16x16x32_bf16 v[16:19], v[128:131], v[194:197], v[16:19]
	v_mfma_f32_16x16x32_bf16 v[8:11], v[136:139], v[194:197], v[8:11]
	v_mfma_f32_16x16x32_bf16 v[60:63], v[132:135], v[166:169], v[60:63]
	v_mfma_f32_16x16x32_bf16 v[56:59], v[146:149], v[166:169], v[56:59]
	v_mfma_f32_16x16x32_bf16 v[48:51], v[132:135], v[174:177], v[48:51]
	v_mfma_f32_16x16x32_bf16 v[40:43], v[146:149], v[174:177], v[40:43]
	v_mfma_f32_16x16x32_bf16 v[32:35], v[132:135], v[182:185], v[32:35]
	v_mfma_f32_16x16x32_bf16 v[24:27], v[146:149], v[182:185], v[24:27]
	v_mfma_f32_16x16x32_bf16 v[16:19], v[132:135], v[210:213], v[16:19]
	v_mfma_f32_16x16x32_bf16 v[8:11], v[146:149], v[210:213], v[8:11]
	v_mfma_f32_16x16x32_bf16 v[52:55], v[214:217], v[162:165], v[52:55]
	v_mfma_f32_16x16x32_bf16 v[44:47], v[222:225], v[162:165], v[44:47]
	v_mfma_f32_16x16x32_bf16 v[36:39], v[214:217], v[170:173], v[36:39]
	v_mfma_f32_16x16x32_bf16 v[28:31], v[222:225], v[170:173], v[28:31]
	v_mfma_f32_16x16x32_bf16 v[20:23], v[214:217], v[178:181], v[20:23]
	v_mfma_f32_16x16x32_bf16 v[12:15], v[222:225], v[178:181], v[12:15]
	v_mfma_f32_16x16x32_bf16 v[4:7], v[214:217], v[194:197], v[4:7]
	v_mfma_f32_16x16x32_bf16 v[0:3], v[222:225], v[194:197], v[0:3]
	v_mfma_f32_16x16x32_bf16 v[52:55], v[218:221], v[166:169], v[52:55]
	v_mfma_f32_16x16x32_bf16 v[44:47], v[226:229], v[166:169], v[44:47]
	v_mfma_f32_16x16x32_bf16 v[36:39], v[218:221], v[174:177], v[36:39]
	v_mfma_f32_16x16x32_bf16 v[28:31], v[226:229], v[174:177], v[28:31]
	v_mfma_f32_16x16x32_bf16 v[20:23], v[218:221], v[182:185], v[20:23]
	v_mfma_f32_16x16x32_bf16 v[12:15], v[226:229], v[182:185], v[12:15]
	v_mfma_f32_16x16x32_bf16 v[4:7], v[218:221], v[210:213], v[4:7]
	v_mfma_f32_16x16x32_bf16 v[0:3], v[226:229], v[210:213], v[0:3]
	s_barrier
	s_add_i32 s6, 0, 0x18000
	v_add_u32_e32 v146, s6, v206
	ds_read_b128 v[128:131], v146
	ds_read_b128 v[132:135], v146 offset:1024
	ds_read_b128 v[136:139], v146 offset:2048
	ds_read_b128 v[146:149], v146 offset:3072
	s_add_u32 s58, s58, 0x40000
	s_addc_u32 s59, s59, 0
	s_mov_b32 m0, s70
	v_lshl_add_u64 v[214:215], s[58:59], 0, v[154:155]
	ds_read_b128 v[162:165], v208 offset:32768
	ds_read_b128 v[166:169], v208 offset:33792
	ds_read_b128 v[170:173], v208 offset:34816
	ds_read_b128 v[174:177], v208 offset:35840
	ds_read_b128 v[178:181], v208 offset:36864
	ds_read_b128 v[182:185], v208 offset:37888
	ds_read_b128 v[194:197], v208 offset:38912
	ds_read_b128 v[210:213], v208 offset:39936
	global_load_lds_dwordx4 v[214:215], off
	v_lshl_add_u64 v[214:215], s[58:59], 0, v[152:153]
	s_mov_b32 m0, s71
	s_nop 0
	global_load_lds_dwordx4 v[214:215], off
	s_add_i32 s19, 0, 0x1c000
	v_add_u32_e32 v192, s19, v206
	ds_read_b128 v[214:217], v192
	ds_read_b128 v[218:221], v192 offset:1024
	ds_read_b128 v[222:225], v192 offset:2048
	ds_read_b128 v[226:229], v192 offset:3072
	s_waitcnt vmcnt(8)
	s_waitcnt lgkmcnt(0)
	s_barrier
	v_mfma_f32_16x16x32_bf16 v[124:127], v[128:131], v[162:165], v[124:127]
	v_mfma_f32_16x16x32_bf16 v[120:123], v[136:139], v[162:165], v[120:123]
	v_mfma_f32_16x16x32_bf16 v[108:111], v[128:131], v[170:173], v[108:111]
	v_mfma_f32_16x16x32_bf16 v[104:107], v[136:139], v[170:173], v[104:107]
	v_mfma_f32_16x16x32_bf16 v[96:99], v[128:131], v[178:181], v[96:99]
	v_mfma_f32_16x16x32_bf16 v[88:91], v[136:139], v[178:181], v[88:91]
	v_mfma_f32_16x16x32_bf16 v[84:87], v[128:131], v[194:197], v[84:87]
	v_mfma_f32_16x16x32_bf16 v[80:83], v[136:139], v[194:197], v[80:83]
	v_mfma_f32_16x16x32_bf16 v[124:127], v[132:135], v[166:169], v[124:127]
	v_mfma_f32_16x16x32_bf16 v[120:123], v[146:149], v[166:169], v[120:123]
	v_mfma_f32_16x16x32_bf16 v[108:111], v[132:135], v[174:177], v[108:111]
	v_mfma_f32_16x16x32_bf16 v[104:107], v[146:149], v[174:177], v[104:107]
	v_mfma_f32_16x16x32_bf16 v[96:99], v[132:135], v[182:185], v[96:99]
	v_mfma_f32_16x16x32_bf16 v[88:91], v[146:149], v[182:185], v[88:91]
	v_mfma_f32_16x16x32_bf16 v[84:87], v[132:135], v[210:213], v[84:87]
	v_mfma_f32_16x16x32_bf16 v[80:83], v[146:149], v[210:213], v[80:83]
	v_mfma_f32_16x16x32_bf16 v[116:119], v[214:217], v[162:165], v[116:119]
	v_mfma_f32_16x16x32_bf16 v[112:115], v[222:225], v[162:165], v[112:115]
	v_mfma_f32_16x16x32_bf16 v[100:103], v[214:217], v[170:173], v[100:103]
	v_mfma_f32_16x16x32_bf16 v[92:95], v[222:225], v[170:173], v[92:95]
	v_mfma_f32_16x16x32_bf16 v[76:79], v[214:217], v[178:181], v[76:79]
	v_mfma_f32_16x16x32_bf16 v[72:75], v[222:225], v[178:181], v[72:75]
	v_mfma_f32_16x16x32_bf16 v[68:71], v[214:217], v[194:197], v[68:71]
	v_mfma_f32_16x16x32_bf16 v[64:67], v[222:225], v[194:197], v[64:67]
	v_mfma_f32_16x16x32_bf16 v[116:119], v[218:221], v[166:169], v[116:119]
	v_mfma_f32_16x16x32_bf16 v[112:115], v[226:229], v[166:169], v[112:115]
	v_mfma_f32_16x16x32_bf16 v[100:103], v[218:221], v[174:177], v[100:103]
	v_mfma_f32_16x16x32_bf16 v[92:95], v[226:229], v[174:177], v[92:95]
	v_mfma_f32_16x16x32_bf16 v[76:79], v[218:221], v[182:185], v[76:79]
	v_mfma_f32_16x16x32_bf16 v[72:75], v[226:229], v[182:185], v[72:75]
	v_mfma_f32_16x16x32_bf16 v[68:71], v[218:221], v[210:213], v[68:71]
	v_mfma_f32_16x16x32_bf16 v[64:67], v[226:229], v[210:213], v[64:67]
	s_barrier
	s_add_i32 s6, s6, s57
	v_lshl_add_u64 v[230:231], v[230:231], 0, s[36:37]
	s_mov_b32 m0, s6
	s_nop 0
	global_load_lds_dwordx4 v[230:231], off
	v_lshl_add_u64 v[230:231], v[232:233], 0, s[36:37]
	s_add_i32 m0, s6, 0x2000
	s_nop 0
	global_load_lds_dwordx4 v[230:231], off
	s_mov_b32 m0, s72
	v_lshl_add_u64 v[230:231], v[234:235], 0, s[36:37]
	ds_read_b128 v[162:165], v208 offset:49152
	ds_read_b128 v[166:169], v208 offset:50176
	ds_read_b128 v[170:173], v208 offset:51200
	ds_read_b128 v[174:177], v208 offset:52224
	ds_read_b128 v[178:181], v208 offset:53248
	ds_read_b128 v[182:185], v208 offset:54272
	ds_read_b128 v[194:197], v208 offset:55296
	ds_read_b128 v[210:213], v208 offset:56320
	global_load_lds_dwordx4 v[230:231], off
	v_lshl_add_u64 v[230:231], v[236:237], 0, s[36:37]
	s_mov_b32 m0, s73
	s_nop 0
	global_load_lds_dwordx4 v[230:231], off
	s_add_u32 s54, s54, 0x40080
	s_addc_u32 s55, s55, 0
	s_add_i32 s6, s19, s57
	v_lshl_add_u64 v[250:251], s[54:55], 0, v[140:141]
	s_mov_b32 m0, s6
	s_nop 0
	global_load_lds_dwordx4 v[250:251], off
	v_lshl_add_u64 v[250:251], s[54:55], 0, v[150:151]
	s_add_i32 m0, s6, 0x2000
	s_nop 0
	global_load_lds_dwordx4 v[250:251], off
	s_waitcnt vmcnt(8)
	s_waitcnt lgkmcnt(0)
	s_barrier
	v_mfma_f32_16x16x32_bf16 v[60:63], v[128:131], v[162:165], v[60:63]
	v_mfma_f32_16x16x32_bf16 v[56:59], v[136:139], v[162:165], v[56:59]
	v_mfma_f32_16x16x32_bf16 v[48:51], v[128:131], v[170:173], v[48:51]
	v_mfma_f32_16x16x32_bf16 v[40:43], v[136:139], v[170:173], v[40:43]
	v_mfma_f32_16x16x32_bf16 v[32:35], v[128:131], v[178:181], v[32:35]
	v_mfma_f32_16x16x32_bf16 v[24:27], v[136:139], v[178:181], v[24:27]
	v_mfma_f32_16x16x32_bf16 v[16:19], v[128:131], v[194:197], v[16:19]
	v_mfma_f32_16x16x32_bf16 v[8:11], v[136:139], v[194:197], v[8:11]
	v_mfma_f32_16x16x32_bf16 v[60:63], v[132:135], v[166:169], v[60:63]
	v_mfma_f32_16x16x32_bf16 v[56:59], v[146:149], v[166:169], v[56:59]
	v_mfma_f32_16x16x32_bf16 v[48:51], v[132:135], v[174:177], v[48:51]
	v_mfma_f32_16x16x32_bf16 v[40:43], v[146:149], v[174:177], v[40:43]
	v_mfma_f32_16x16x32_bf16 v[32:35], v[132:135], v[182:185], v[32:35]
	v_mfma_f32_16x16x32_bf16 v[24:27], v[146:149], v[182:185], v[24:27]
	v_mfma_f32_16x16x32_bf16 v[16:19], v[132:135], v[210:213], v[16:19]
	v_mfma_f32_16x16x32_bf16 v[8:11], v[146:149], v[210:213], v[8:11]
	v_mfma_f32_16x16x32_bf16 v[52:55], v[214:217], v[162:165], v[52:55]
	v_mfma_f32_16x16x32_bf16 v[44:47], v[222:225], v[162:165], v[44:47]
	v_mfma_f32_16x16x32_bf16 v[36:39], v[214:217], v[170:173], v[36:39]
	v_mfma_f32_16x16x32_bf16 v[28:31], v[222:225], v[170:173], v[28:31]
	v_mfma_f32_16x16x32_bf16 v[20:23], v[214:217], v[178:181], v[20:23]
	v_mfma_f32_16x16x32_bf16 v[12:15], v[222:225], v[178:181], v[12:15]
	v_mfma_f32_16x16x32_bf16 v[4:7], v[214:217], v[194:197], v[4:7]
	v_mfma_f32_16x16x32_bf16 v[0:3], v[222:225], v[194:197], v[0:3]
	v_mfma_f32_16x16x32_bf16 v[52:55], v[218:221], v[166:169], v[52:55]
	v_mfma_f32_16x16x32_bf16 v[44:47], v[226:229], v[166:169], v[44:47]
	v_mfma_f32_16x16x32_bf16 v[36:39], v[218:221], v[174:177], v[36:39]
	v_mfma_f32_16x16x32_bf16 v[28:31], v[226:229], v[174:177], v[28:31]
	v_mfma_f32_16x16x32_bf16 v[20:23], v[218:221], v[182:185], v[20:23]
	v_mfma_f32_16x16x32_bf16 v[12:15], v[226:229], v[182:185], v[12:15]
	v_mfma_f32_16x16x32_bf16 v[4:7], v[218:221], v[210:213], v[4:7]
	v_mfma_f32_16x16x32_bf16 v[0:3], v[226:229], v[210:213], v[0:3]
	s_add_i32 s82, s82, 2
	s_add_u32 s52, s52, 0x100
	s_addc_u32 s53, s53, 0
	s_add_u32 s39, s39, 0x100
	s_addc_u32 s51, s51, 0
	s_cmp_gt_u32 s82, 13
	s_barrier
	s_cbranch_scc0 .LBB0_248
	s_mov_b32 s100, 1
	s_ashr_i32 s51, s50, 31
	v_lshl_or_b32 v128, s81, 8, v207
	s_lshl_b64 s[10:11], s[50:51], 8
	v_ashrrev_i32_e32 v129, 31, v128
	v_lshl_add_u64 v[168:169], s[10:11], 0, v[156:157]
	v_lshlrev_b64 v[170:171], 1, v[128:129]
	v_lshl_add_u64 v[174:175], s[28:29], 0, v[170:171]
	v_lshlrev_b64 v[172:173], 11, v[168:169]
	v_lshl_add_u64 v[128:129], v[174:175], 0, v[172:173]
	global_load_dwordx4 v[146:149], v[128:129], off
	global_load_dwordx4 v[182:185], v[128:129], off offset:256
	v_or_b32_e32 v166, 16, v168
	v_mov_b32_e32 v167, v169
	v_lshlrev_b64 v[176:177], 11, v[166:167]
	v_lshl_add_u64 v[128:129], v[174:175], 0, v[176:177]
	global_load_dwordx4 v[194:197], v[128:129], off
	global_load_dwordx4 v[210:213], v[128:129], off offset:256
	v_or_b32_e32 v164, 32, v168
	v_mov_b32_e32 v165, v169
	v_or_b32_e32 v162, 48, v168
	v_mov_b32_e32 v163, v169
	v_lshlrev_b64 v[180:181], 11, v[164:165]
	v_lshlrev_b64 v[178:179], 11, v[162:163]
	v_lshl_add_u64 v[128:129], v[174:175], 0, v[180:181]
	v_lshl_add_u64 v[130:131], v[174:175], 0, v[178:179]
	global_load_dwordx4 v[214:217], v[128:129], off
	global_load_dwordx4 v[136:139], v[128:129], off offset:256
	global_load_dwordx4 v[132:135], v[130:131], off
	s_nop 0
	global_load_dwordx4 v[128:131], v[130:131], off offset:256
	s_mov_b64 s[10:11], 0x90
	v_lshl_add_u64 v[172:173], s[30:31], 0, v[172:173]
	v_lshl_add_u64 v[172:173], v[172:173], 0, v[170:171]
	s_waitcnt vmcnt(0)
	v_lshlrev_b32_e32 v218, 16, v146
	v_and_b32_e32 v219, 0xffff0000, v146
	v_lshlrev_b32_e32 v220, 16, v148
	v_and_b32_e32 v221, 0xffff0000, v148
	v_lshlrev_b32_e32 v146, 16, v147
	v_and_b32_e32 v147, 0xffff0000, v147
	v_lshlrev_b32_e32 v222, 16, v182
	v_and_b32_e32 v223, 0xffff0000, v182
	v_lshlrev_b32_e32 v224, 16, v184
	v_and_b32_e32 v225, 0xffff0000, v184
	v_lshlrev_b32_e32 v182, 16, v183
	v_and_b32_e32 v183, 0xffff0000, v183
	v_pk_add_f32 v[124:125], v[124:125], v[218:219]
	v_pk_add_f32 v[120:121], v[120:121], v[220:221]
	v_pk_add_f32 v[126:127], v[126:127], v[146:147]
	v_pk_add_f32 v[116:117], v[116:117], v[222:223]
	v_pk_add_f32 v[146:147], v[112:113], v[224:225]
	v_pk_add_f32 v[118:119], v[118:119], v[182:183]
	v_pk_mul_f32 v[220:221], v[124:125], v[124:125]
	v_pk_mul_f32 v[222:223], v[126:127], v[126:127]
	v_cvt_pk_bf16_f32 v112, v124, v125
	v_cvt_pk_bf16_f32 v113, v126, v127
	v_pk_mul_f32 v[124:125], v[116:117], v[116:117]
	v_pk_mul_f32 v[126:127], v[118:119], v[118:119]
	v_pk_mul_f32 v[228:229], v[146:147], v[146:147]
	v_cvt_pk_bf16_f32 v116, v116, v117
	v_cvt_pk_bf16_f32 v117, v118, v119
	v_cvt_pk_bf16_f32 v118, v146, v147
	v_add_f32_e32 v146, v220, v221
	v_add_f32_e32 v146, v222, v146
	v_lshlrev_b32_e32 v148, 16, v149
	v_and_b32_e32 v149, 0xffff0000, v149
	v_pk_mul_f32 v[224:225], v[120:121], v[120:121]
	v_add_f32_e32 v146, v223, v146
	v_pk_add_f32 v[122:123], v[122:123], v[148:149]
	v_add_f32_e32 v146, v224, v146
	v_pk_mul_f32 v[226:227], v[122:123], v[122:123]
	v_add_f32_e32 v146, v225, v146
	v_add_f32_e32 v146, v226, v146
	v_add_f32_e32 v146, v227, v146
	v_add_f32_e32 v124, v124, v146
	v_add_f32_e32 v124, v125, v124
	v_add_f32_e32 v124, v126, v124
	v_lshlrev_b32_e32 v184, 16, v185
	v_and_b32_e32 v185, 0xffff0000, v185
	v_add_f32_e32 v124, v127, v124
	v_pk_add_f32 v[148:149], v[114:115], v[184:185]
	v_add_f32_e32 v124, v228, v124
	v_pk_mul_f32 v[230:231], v[148:149], v[148:149]
	v_add_f32_e32 v124, v229, v124
	v_add_f32_e32 v124, v230, v124
	v_add_f32_e32 v209, v231, v124
	v_lshlrev_b32_e32 v124, 16, v212
	v_and_b32_e32 v125, 0xffff0000, v212
	v_pk_add_f32 v[124:125], v[92:93], v[124:125]
	v_lshlrev_b32_e32 v92, 16, v211
	v_and_b32_e32 v93, 0xffff0000, v211
	v_pk_add_f32 v[102:103], v[102:103], v[92:93]
	v_lshlrev_b32_e32 v92, 16, v213
	v_and_b32_e32 v93, 0xffff0000, v213
	v_pk_add_f32 v[126:127], v[94:95], v[92:93]
	v_lshlrev_b32_e32 v92, 16, v214
	v_and_b32_e32 v93, 0xffff0000, v214
	v_pk_add_f32 v[92:93], v[96:97], v[92:93]
	v_lshlrev_b32_e32 v96, 16, v217
	v_and_b32_e32 v97, 0xffff0000, v217
	v_lshlrev_b32_e32 v94, 16, v216
	v_and_b32_e32 v95, 0xffff0000, v216
	v_pk_add_f32 v[90:91], v[90:91], v[96:97]
	v_lshlrev_b32_e32 v96, 16, v136
	v_and_b32_e32 v97, 0xffff0000, v136
	v_lshlrev_b32_e32 v182, 16, v194
	v_and_b32_e32 v183, 0xffff0000, v194
	v_pk_add_f32 v[88:89], v[88:89], v[94:95]
	v_lshlrev_b32_e32 v94, 16, v215
	v_and_b32_e32 v95, 0xffff0000, v215
	v_pk_add_f32 v[96:97], v[76:77], v[96:97]
	v_lshl_add_u64 v[76:77], v[168:169], 0, s[36:37]
	v_lshlrev_b32_e32 v184, 16, v196
	v_and_b32_e32 v185, 0xffff0000, v196
	v_cvt_pk_bf16_f32 v114, v120, v121
	v_pk_add_f32 v[120:121], v[108:109], v[182:183]
	v_pk_add_f32 v[94:95], v[98:99], v[94:95]
	v_lshlrev_b64 v[182:183], 11, v[76:77]
	v_lshlrev_b32_e32 v98, 16, v138
	v_and_b32_e32 v99, 0xffff0000, v138
	v_pk_add_f32 v[108:109], v[104:105], v[184:185]
	v_lshl_add_u64 v[184:185], v[174:175], 0, v[182:183]
	v_pk_add_f32 v[98:99], v[72:73], v[98:99]
	v_lshlrev_b32_e32 v72, 16, v137
	v_and_b32_e32 v73, 0xffff0000, v137
	v_lshlrev_b32_e32 v218, 16, v210
	v_and_b32_e32 v219, 0xffff0000, v210
	global_load_dwordx4 v[210:213], v[184:185], off
	v_pk_add_f32 v[136:137], v[78:79], v[72:73]
	v_lshlrev_b32_e32 v72, 16, v139
	v_and_b32_e32 v73, 0xffff0000, v139
	v_pk_add_f32 v[138:139], v[74:75], v[72:73]
	v_lshlrev_b32_e32 v72, 16, v132
	v_and_b32_e32 v73, 0xffff0000, v132
	v_pk_add_f32 v[74:75], v[84:85], v[72:73]
	v_lshlrev_b32_e32 v72, 16, v134
	v_and_b32_e32 v73, 0xffff0000, v134
	v_pk_add_f32 v[78:79], v[80:81], v[72:73]
	v_lshlrev_b32_e32 v72, 16, v133
	v_and_b32_e32 v73, 0xffff0000, v133
	v_pk_add_f32 v[100:101], v[100:101], v[218:219]
	global_load_dwordx4 v[218:221], v[184:185], off offset:256
	v_pk_add_f32 v[80:81], v[86:87], v[72:73]
	v_lshlrev_b32_e32 v72, 16, v135
	v_and_b32_e32 v73, 0xffff0000, v135
	v_pk_add_f32 v[82:83], v[82:83], v[72:73]
	v_lshl_add_u64 v[72:73], v[168:169], 0, s[10:11]
	v_lshlrev_b64 v[132:133], 11, v[72:73]
	v_lshl_add_u64 v[134:135], v[174:175], 0, v[132:133]
	v_lshlrev_b32_e32 v84, 16, v128
	v_and_b32_e32 v85, 0xffff0000, v128
	global_load_dwordx4 v[226:229], v[134:135], off
	global_load_dwordx4 v[234:237], v[134:135], off offset:256
	v_pk_add_f32 v[84:85], v[68:69], v[84:85]
	v_lshlrev_b32_e32 v68, 16, v130
	v_and_b32_e32 v69, 0xffff0000, v130
	v_pk_add_f32 v[86:87], v[64:65], v[68:69]
	v_lshlrev_b32_e32 v64, 16, v129
	v_and_b32_e32 v65, 0xffff0000, v129
	s_mov_b64 s[10:11], 0xa0
	v_pk_add_f32 v[128:129], v[70:71], v[64:65]
	v_lshl_add_u64 v[70:71], v[168:169], 0, s[10:11]
	s_mov_b64 s[10:11], 0xb0
	v_lshlrev_b32_e32 v64, 16, v131
	v_and_b32_e32 v65, 0xffff0000, v131
	v_lshlrev_b64 v[134:135], 11, v[70:71]
	v_lshl_add_u64 v[68:69], v[168:169], 0, s[10:11]
	v_pk_add_f32 v[130:131], v[66:67], v[64:65]
	v_lshl_add_u64 v[64:65], v[174:175], 0, v[134:135]
	v_lshlrev_b64 v[184:185], 11, v[68:69]
	global_load_dwordx4 v[238:241], v[64:65], off
	global_load_dwordx4 v[242:245], v[64:65], off offset:256
	v_lshl_add_u64 v[64:65], v[174:175], 0, v[184:185]
	global_load_dwordx4 v[246:249], v[64:65], off
	s_nop 0
	global_load_dwordx4 v[64:67], v[64:65], off offset:256
	v_lshlrev_b32_e32 v194, 16, v195
	v_and_b32_e32 v195, 0xffff0000, v195
	v_lshlrev_b32_e32 v196, 16, v197
	v_and_b32_e32 v197, 0xffff0000, v197
	v_cvt_pk_bf16_f32 v115, v122, v123
	v_cvt_pk_bf16_f32 v119, v148, v149
	v_pk_add_f32 v[122:123], v[110:111], v[194:195]
	v_pk_add_f32 v[110:111], v[106:107], v[196:197]
	global_store_dwordx4 v[172:173], v[112:115], off
	global_store_dwordx4 v[172:173], v[116:119], off offset:256
	v_cvt_pk_bf16_f32 v104, v120, v121
	v_lshl_add_u64 v[112:113], s[30:31], 0, v[176:177]
	v_cvt_pk_bf16_f32 v105, v122, v123
	v_cvt_pk_bf16_f32 v106, v108, v109
	v_cvt_pk_bf16_f32 v107, v110, v111
	v_lshl_add_u64 v[112:113], v[112:113], 0, v[170:171]
	v_cvt_pk_bf16_f32 v146, v100, v101
	v_cvt_pk_bf16_f32 v147, v102, v103
	v_cvt_pk_bf16_f32 v148, v124, v125
	v_cvt_pk_bf16_f32 v149, v126, v127
	global_store_dwordx4 v[112:113], v[104:107], off
	global_store_dwordx4 v[112:113], v[146:149], off offset:256
	v_cvt_pk_bf16_f32 v194, v92, v93
	v_lshl_add_u64 v[104:105], s[30:31], 0, v[180:181]
	v_cvt_pk_bf16_f32 v195, v94, v95
	v_cvt_pk_bf16_f32 v196, v88, v89
	v_cvt_pk_bf16_f32 v197, v90, v91
	v_lshl_add_u64 v[104:105], v[104:105], 0, v[170:171]
	v_cvt_pk_bf16_f32 v214, v96, v97
	v_cvt_pk_bf16_f32 v215, v136, v137
	v_cvt_pk_bf16_f32 v216, v98, v99
	v_cvt_pk_bf16_f32 v217, v138, v139
	global_store_dwordx4 v[104:105], v[194:197], off
	global_store_dwordx4 v[104:105], v[214:217], off offset:256
	v_lshl_add_u64 v[104:105], s[30:31], 0, v[178:179]
	v_cvt_pk_bf16_f32 v222, v74, v75
	v_cvt_pk_bf16_f32 v223, v80, v81
	v_cvt_pk_bf16_f32 v224, v78, v79
	v_cvt_pk_bf16_f32 v225, v82, v83
	v_lshl_add_u64 v[104:105], v[104:105], 0, v[170:171]
	v_cvt_pk_bf16_f32 v230, v84, v85
	v_cvt_pk_bf16_f32 v231, v128, v129
	v_cvt_pk_bf16_f32 v232, v86, v87
	v_cvt_pk_bf16_f32 v233, v130, v131
	global_store_dwordx4 v[104:105], v[222:225], off
	global_store_dwordx4 v[104:105], v[230:233], off offset:256
	s_waitcnt vmcnt(8)
	v_lshlrev_b32_e32 v104, 16, v210
	v_and_b32_e32 v105, 0xffff0000, v210
	v_pk_add_f32 v[60:61], v[60:61], v[104:105]
	v_lshlrev_b32_e32 v104, 16, v212
	v_and_b32_e32 v105, 0xffff0000, v212
	v_pk_add_f32 v[56:57], v[56:57], v[104:105]
	v_lshlrev_b32_e32 v104, 16, v211
	v_and_b32_e32 v105, 0xffff0000, v211
	v_pk_add_f32 v[62:63], v[62:63], v[104:105]
	v_lshlrev_b32_e32 v104, 16, v213
	v_and_b32_e32 v105, 0xffff0000, v213
	v_pk_add_f32 v[58:59], v[58:59], v[104:105]
	v_lshlrev_b32_e32 v104, 16, v218
	v_and_b32_e32 v105, 0xffff0000, v218
	v_pk_add_f32 v[52:53], v[52:53], v[104:105]
	v_lshlrev_b32_e32 v104, 16, v220
	v_and_b32_e32 v105, 0xffff0000, v220
	v_pk_add_f32 v[104:105], v[44:45], v[104:105]
	v_lshlrev_b32_e32 v44, 16, v219
	v_and_b32_e32 v45, 0xffff0000, v219
	v_pk_add_f32 v[54:55], v[54:55], v[44:45]
	v_lshlrev_b32_e32 v44, 16, v221
	v_and_b32_e32 v45, 0xffff0000, v221
	v_pk_add_f32 v[106:107], v[46:47], v[44:45]
	v_lshlrev_b32_e32 v44, 16, v226
	v_and_b32_e32 v45, 0xffff0000, v226
	v_pk_add_f32 v[44:45], v[48:49], v[44:45]
	v_lshlrev_b32_e32 v48, 16, v229
	v_and_b32_e32 v49, 0xffff0000, v229
	v_pk_add_f32 v[42:43], v[42:43], v[48:49]
	v_lshlrev_b32_e32 v48, 16, v234
	v_and_b32_e32 v49, 0xffff0000, v234
	v_pk_add_f32 v[36:37], v[36:37], v[48:49]
	v_lshlrev_b32_e32 v48, 16, v236
	v_and_b32_e32 v49, 0xffff0000, v236
	v_lshlrev_b32_e32 v46, 16, v228
	v_and_b32_e32 v47, 0xffff0000, v228
	v_pk_add_f32 v[48:49], v[28:29], v[48:49]
	v_lshlrev_b32_e32 v28, 16, v235
	v_and_b32_e32 v29, 0xffff0000, v235
	v_pk_add_f32 v[40:41], v[40:41], v[46:47]
	v_lshlrev_b32_e32 v46, 16, v227
	v_and_b32_e32 v47, 0xffff0000, v227
	v_pk_add_f32 v[38:39], v[38:39], v[28:29]
	v_lshlrev_b32_e32 v28, 16, v237
	v_and_b32_e32 v29, 0xffff0000, v237
	v_pk_add_f32 v[46:47], v[50:51], v[46:47]
	v_pk_add_f32 v[50:51], v[30:31], v[28:29]
	v_lshlrev_b32_e32 v28, 16, v238
	v_and_b32_e32 v29, 0xffff0000, v238
	v_lshlrev_b32_e32 v180, 16, v64
	v_and_b32_e32 v181, 0xffff0000, v64
	v_pk_add_f32 v[28:29], v[32:33], v[28:29]
	v_lshlrev_b32_e32 v32, 16, v241
	v_and_b32_e32 v33, 0xffff0000, v241
	v_pk_add_f32 v[4:5], v[4:5], v[180:181]
	v_lshlrev_b32_e32 v180, 16, v66
	v_and_b32_e32 v181, 0xffff0000, v66
	v_pk_add_f32 v[26:27], v[26:27], v[32:33]
	v_lshlrev_b32_e32 v32, 16, v242
	v_and_b32_e32 v33, 0xffff0000, v242
	v_pk_add_f32 v[0:1], v[0:1], v[180:181]
	v_lshl_add_u64 v[180:181], s[30:31], 0, v[182:183]
	v_cvt_pk_bf16_f32 v112, v60, v61
	v_cvt_pk_bf16_f32 v113, v62, v63
	v_cvt_pk_bf16_f32 v114, v56, v57
	v_cvt_pk_bf16_f32 v115, v58, v59
	v_pk_add_f32 v[20:21], v[20:21], v[32:33]
	v_lshlrev_b32_e32 v32, 16, v244
	v_and_b32_e32 v33, 0xffff0000, v244
	v_lshl_add_u64 v[180:181], v[180:181], 0, v[170:171]
	v_cvt_pk_bf16_f32 v116, v52, v53
	v_cvt_pk_bf16_f32 v117, v54, v55
	v_cvt_pk_bf16_f32 v118, v104, v105
	v_cvt_pk_bf16_f32 v119, v106, v107
	v_lshlrev_b32_e32 v30, 16, v240
	v_and_b32_e32 v31, 0xffff0000, v240
	v_pk_add_f32 v[32:33], v[12:13], v[32:33]
	v_lshlrev_b32_e32 v12, 16, v243
	v_and_b32_e32 v13, 0xffff0000, v243
	global_store_dwordx4 v[180:181], v[112:115], off
	global_store_dwordx4 v[180:181], v[116:119], off offset:256
	v_cvt_pk_bf16_f32 v146, v44, v45
	v_lshl_add_u64 v[112:113], s[30:31], 0, v[132:133]
	v_cvt_pk_bf16_f32 v147, v46, v47
	v_cvt_pk_bf16_f32 v148, v40, v41
	v_cvt_pk_bf16_f32 v149, v42, v43
	v_pk_add_f32 v[24:25], v[24:25], v[30:31]
	v_lshlrev_b32_e32 v30, 16, v239
	v_and_b32_e32 v31, 0xffff0000, v239
	v_pk_add_f32 v[22:23], v[22:23], v[12:13]
	v_lshlrev_b32_e32 v12, 16, v245
	v_and_b32_e32 v13, 0xffff0000, v245
	v_lshl_add_u64 v[112:113], v[112:113], 0, v[170:171]
	v_cvt_pk_bf16_f32 v172, v36, v37
	v_cvt_pk_bf16_f32 v173, v38, v39
	v_cvt_pk_bf16_f32 v174, v48, v49
	v_cvt_pk_bf16_f32 v175, v50, v51
	v_pk_add_f32 v[30:31], v[34:35], v[30:31]
	v_pk_add_f32 v[34:35], v[14:15], v[12:13]
	v_lshlrev_b32_e32 v12, 16, v246
	v_and_b32_e32 v13, 0xffff0000, v246
	v_lshlrev_b32_e32 v14, 16, v248
	v_and_b32_e32 v15, 0xffff0000, v248
	global_store_dwordx4 v[112:113], v[146:149], off
	global_store_dwordx4 v[112:113], v[172:175], off offset:256
	v_lshl_add_u64 v[112:113], s[30:31], 0, v[134:135]
	v_cvt_pk_bf16_f32 v176, v28, v29
	v_cvt_pk_bf16_f32 v177, v30, v31
	v_cvt_pk_bf16_f32 v178, v24, v25
	v_cvt_pk_bf16_f32 v179, v26, v27
	v_pk_add_f32 v[12:13], v[16:17], v[12:13]
	v_pk_add_f32 v[8:9], v[8:9], v[14:15]
	v_lshlrev_b32_e32 v14, 16, v247
	v_and_b32_e32 v15, 0xffff0000, v247
	v_lshlrev_b32_e32 v16, 16, v249
	v_and_b32_e32 v17, 0xffff0000, v249
	v_lshlrev_b32_e32 v64, 16, v65
	v_and_b32_e32 v65, 0xffff0000, v65
	v_lshl_add_u64 v[112:113], v[112:113], 0, v[170:171]
	v_cvt_pk_bf16_f32 v194, v20, v21
	v_cvt_pk_bf16_f32 v195, v22, v23
	v_cvt_pk_bf16_f32 v196, v32, v33
	v_cvt_pk_bf16_f32 v197, v34, v35
	v_pk_add_f32 v[14:15], v[18:19], v[14:15]
	v_pk_add_f32 v[10:11], v[10:11], v[16:17]
	v_pk_add_f32 v[6:7], v[6:7], v[64:65]
	v_lshlrev_b32_e32 v64, 16, v67
	v_and_b32_e32 v65, 0xffff0000, v67
	global_store_dwordx4 v[112:113], v[176:179], off
	global_store_dwordx4 v[112:113], v[194:197], off offset:256
	v_lshl_add_u64 v[112:113], s[30:31], 0, v[184:185]
	v_cvt_pk_bf16_f32 v16, v12, v13
	v_cvt_pk_bf16_f32 v17, v14, v15
	v_cvt_pk_bf16_f32 v18, v8, v9
	v_cvt_pk_bf16_f32 v19, v10, v11
	v_pk_add_f32 v[2:3], v[2:3], v[64:65]
	v_lshl_add_u64 v[112:113], v[112:113], 0, v[170:171]
	v_cvt_pk_bf16_f32 v64, v4, v5
	v_cvt_pk_bf16_f32 v65, v6, v7
	v_cvt_pk_bf16_f32 v66, v0, v1
	v_cvt_pk_bf16_f32 v67, v2, v3
	global_store_dwordx4 v[112:113], v[16:19], off
	global_store_dwordx4 v[112:113], v[64:67], off offset:256
	s_lshl_b32 s10, s81, 2
	v_and_b32_e32 v17, 64, v188
	v_xor_b32_e32 v16, 16, v188
	v_add_u32_e32 v17, 64, v17
	v_cmp_lt_i32_e32 vcc, v16, v17
	v_xor_b32_e32 v18, 32, v188
	s_ashr_i32 s11, s10, 31
	v_cndmask_b32_e32 v16, v188, v16, vcc
	v_lshlrev_b32_e32 v16, 2, v16
	ds_bpermute_b32 v19, v16, v209
	v_cmp_lt_i32_e32 vcc, v18, v17
	s_lshl_b64 s[10:11], s[10:11], 2
	s_add_u32 s50, s75, s10
	v_cndmask_b32_e32 v17, v188, v18, vcc
	v_lshlrev_b32_e32 v17, 2, v17
	s_waitcnt lgkmcnt(0)
	v_add_f32_e32 v18, v209, v19
	ds_bpermute_b32 v19, v17, v18
	s_addc_u32 s51, s80, s11
	s_and_saveexec_b64 s[52:53], s[42:43]
	s_cbranch_execz .LBB0_251
	s_waitcnt lgkmcnt(0)
	v_add_f32_e32 v64, v18, v19
	v_lshlrev_b64 v[18:19], 6, v[168:169]
	v_lshl_add_u64 v[18:19], s[50:51], 0, v[18:19]
	global_store_dword v[18:19], v64, off

.LBB0_341:
	s_add_u32 s46, s50, 0x100
	s_addc_u32 s47, s51, 0
	s_add_i32 s6, 0, 0x10000
	v_add_u32_e32 v146, s6, v206
	ds_read_b128 v[128:131], v146
	ds_read_b128 v[132:135], v146 offset:1024
	ds_read_b128 v[136:139], v146 offset:2048
	ds_read_b128 v[146:149], v146 offset:3072
	s_cmp_eq_u32 s12, 40
	s_cselect_b32 s53, s31, s47
	s_cselect_b32 s52, s30, s46
	s_cselect_b32 s49, s35, s11
	s_cselect_b32 s48, s34, s10
	v_lshl_add_u64 v[214:215], s[50:51], 0, v[158:159]
	s_add_i32 m0, s58, 0xc000
	ds_read_b128 v[162:165], v208
	ds_read_b128 v[166:169], v208 offset:1024
	ds_read_b128 v[170:173], v208 offset:2048
	ds_read_b128 v[174:177], v208 offset:3072
	ds_read_b128 v[178:181], v208 offset:4096
	ds_read_b128 v[182:185], v208 offset:5120
	ds_read_b128 v[194:197], v208 offset:6144
	ds_read_b128 v[210:213], v208 offset:7168
	global_load_lds_dwordx4 v[214:215], off
	v_lshl_add_u64 v[214:215], s[50:51], 0, v[160:161]
	s_add_i32 m0, s58, 0xe000
	s_nop 0
	global_load_lds_dwordx4 v[214:215], off
	s_add_i32 s19, 0, 0x14000
	v_add_u32_e32 v192, s19, v206
	ds_read_b128 v[214:217], v192
	ds_read_b128 v[218:221], v192 offset:1024
	ds_read_b128 v[222:225], v192 offset:2048
	ds_read_b128 v[226:229], v192 offset:3072
	s_waitcnt vmcnt(8)
	s_waitcnt lgkmcnt(0)
	s_barrier
	v_mfma_f32_16x16x32_bf16 v[124:127], v[128:131], v[162:165], v[124:127]
	v_mfma_f32_16x16x32_bf16 v[120:123], v[136:139], v[162:165], v[120:123]
	v_mfma_f32_16x16x32_bf16 v[108:111], v[128:131], v[170:173], v[108:111]
	v_mfma_f32_16x16x32_bf16 v[104:107], v[136:139], v[170:173], v[104:107]
	v_mfma_f32_16x16x32_bf16 v[96:99], v[128:131], v[178:181], v[96:99]
	v_mfma_f32_16x16x32_bf16 v[88:91], v[136:139], v[178:181], v[88:91]
	v_mfma_f32_16x16x32_bf16 v[84:87], v[128:131], v[194:197], v[84:87]
	v_mfma_f32_16x16x32_bf16 v[80:83], v[136:139], v[194:197], v[80:83]
	v_mfma_f32_16x16x32_bf16 v[124:127], v[132:135], v[166:169], v[124:127]
	v_mfma_f32_16x16x32_bf16 v[120:123], v[146:149], v[166:169], v[120:123]
	v_mfma_f32_16x16x32_bf16 v[108:111], v[132:135], v[174:177], v[108:111]
	v_mfma_f32_16x16x32_bf16 v[104:107], v[146:149], v[174:177], v[104:107]
	v_mfma_f32_16x16x32_bf16 v[96:99], v[132:135], v[182:185], v[96:99]
	v_mfma_f32_16x16x32_bf16 v[88:91], v[146:149], v[182:185], v[88:91]
	v_mfma_f32_16x16x32_bf16 v[84:87], v[132:135], v[210:213], v[84:87]
	v_mfma_f32_16x16x32_bf16 v[80:83], v[146:149], v[210:213], v[80:83]
	v_mfma_f32_16x16x32_bf16 v[116:119], v[214:217], v[162:165], v[116:119]
	v_mfma_f32_16x16x32_bf16 v[112:115], v[222:225], v[162:165], v[112:115]
	v_mfma_f32_16x16x32_bf16 v[100:103], v[214:217], v[170:173], v[100:103]
	v_mfma_f32_16x16x32_bf16 v[92:95], v[222:225], v[170:173], v[92:95]
	v_mfma_f32_16x16x32_bf16 v[76:79], v[214:217], v[178:181], v[76:79]
	v_mfma_f32_16x16x32_bf16 v[72:75], v[222:225], v[178:181], v[72:75]
	v_mfma_f32_16x16x32_bf16 v[68:71], v[214:217], v[194:197], v[68:71]
	v_mfma_f32_16x16x32_bf16 v[64:67], v[222:225], v[194:197], v[64:67]
	v_mfma_f32_16x16x32_bf16 v[116:119], v[218:221], v[166:169], v[116:119]
	v_mfma_f32_16x16x32_bf16 v[112:115], v[226:229], v[166:169], v[112:115]
	v_mfma_f32_16x16x32_bf16 v[100:103], v[218:221], v[174:177], v[100:103]
	v_mfma_f32_16x16x32_bf16 v[92:95], v[226:229], v[174:177], v[92:95]
	v_mfma_f32_16x16x32_bf16 v[76:79], v[218:221], v[182:185], v[76:79]
	v_mfma_f32_16x16x32_bf16 v[72:75], v[226:229], v[182:185], v[72:75]
	v_mfma_f32_16x16x32_bf16 v[68:71], v[218:221], v[210:213], v[68:71]
	v_mfma_f32_16x16x32_bf16 v[64:67], v[226:229], v[210:213], v[64:67]
	s_barrier
	s_add_i32 s6, s6, s57
	v_lshl_add_u64 v[230:231], s[48:49], 0, v[140:141]
	s_mov_b32 m0, s6
	s_nop 0
	global_load_lds_dwordx4 v[230:231], off
	v_lshl_add_u64 v[232:233], s[48:49], 0, v[150:151]
	s_add_i32 m0, s6, 0x2000
	s_nop 0
	global_load_lds_dwordx4 v[232:233], off
	s_mov_b32 m0, s58
	v_lshl_add_u64 v[234:235], s[52:53], 0, v[154:155]
	ds_read_b128 v[162:165], v208 offset:16384
	ds_read_b128 v[166:169], v208 offset:17408
	ds_read_b128 v[170:173], v208 offset:18432
	ds_read_b128 v[174:177], v208 offset:19456
	ds_read_b128 v[178:181], v208 offset:20480
	ds_read_b128 v[182:185], v208 offset:21504
	ds_read_b128 v[194:197], v208 offset:22528
	ds_read_b128 v[210:213], v208 offset:23552
	global_load_lds_dwordx4 v[234:235], off
	v_lshl_add_u64 v[236:237], s[52:53], 0, v[152:153]
	s_mov_b32 m0, s59
	s_nop 0
	global_load_lds_dwordx4 v[236:237], off
	s_add_u32 s50, s48, 0xb0000
	s_addc_u32 s51, s49, 0
	s_add_i32 s6, s19, s57
	v_lshl_add_u64 v[250:251], s[50:51], 0, v[140:141]
	s_mov_b32 m0, s6
	s_nop 0
	global_load_lds_dwordx4 v[250:251], off
	v_lshl_add_u64 v[250:251], s[50:51], 0, v[150:151]
	s_add_i32 m0, s6, 0x2000
	s_nop 0
	global_load_lds_dwordx4 v[250:251], off
	s_waitcnt vmcnt(8)
	s_waitcnt lgkmcnt(0)
	s_barrier
	v_mfma_f32_16x16x32_bf16 v[60:63], v[128:131], v[162:165], v[60:63]
	v_mfma_f32_16x16x32_bf16 v[56:59], v[136:139], v[162:165], v[56:59]
	v_mfma_f32_16x16x32_bf16 v[48:51], v[128:131], v[170:173], v[48:51]
	v_mfma_f32_16x16x32_bf16 v[40:43], v[136:139], v[170:173], v[40:43]
	v_mfma_f32_16x16x32_bf16 v[32:35], v[128:131], v[178:181], v[32:35]
	v_mfma_f32_16x16x32_bf16 v[24:27], v[136:139], v[178:181], v[24:27]
	v_mfma_f32_16x16x32_bf16 v[16:19], v[128:131], v[194:197], v[16:19]
	v_mfma_f32_16x16x32_bf16 v[8:11], v[136:139], v[194:197], v[8:11]
	v_mfma_f32_16x16x32_bf16 v[60:63], v[132:135], v[166:169], v[60:63]
	v_mfma_f32_16x16x32_bf16 v[56:59], v[146:149], v[166:169], v[56:59]
	v_mfma_f32_16x16x32_bf16 v[48:51], v[132:135], v[174:177], v[48:51]
	v_mfma_f32_16x16x32_bf16 v[40:43], v[146:149], v[174:177], v[40:43]
	v_mfma_f32_16x16x32_bf16 v[32:35], v[132:135], v[182:185], v[32:35]
	v_mfma_f32_16x16x32_bf16 v[24:27], v[146:149], v[182:185], v[24:27]
	v_mfma_f32_16x16x32_bf16 v[16:19], v[132:135], v[210:213], v[16:19]
	v_mfma_f32_16x16x32_bf16 v[8:11], v[146:149], v[210:213], v[8:11]
	v_mfma_f32_16x16x32_bf16 v[52:55], v[214:217], v[162:165], v[52:55]
	v_mfma_f32_16x16x32_bf16 v[44:47], v[222:225], v[162:165], v[44:47]
	v_mfma_f32_16x16x32_bf16 v[36:39], v[214:217], v[170:173], v[36:39]
	v_mfma_f32_16x16x32_bf16 v[28:31], v[222:225], v[170:173], v[28:31]
	v_mfma_f32_16x16x32_bf16 v[20:23], v[214:217], v[178:181], v[20:23]
	v_mfma_f32_16x16x32_bf16 v[12:15], v[222:225], v[178:181], v[12:15]
	v_mfma_f32_16x16x32_bf16 v[4:7], v[214:217], v[194:197], v[4:7]
	v_mfma_f32_16x16x32_bf16 v[0:3], v[222:225], v[194:197], v[0:3]
	v_mfma_f32_16x16x32_bf16 v[52:55], v[218:221], v[166:169], v[52:55]
	v_mfma_f32_16x16x32_bf16 v[44:47], v[226:229], v[166:169], v[44:47]
	v_mfma_f32_16x16x32_bf16 v[36:39], v[218:221], v[174:177], v[36:39]
	v_mfma_f32_16x16x32_bf16 v[28:31], v[226:229], v[174:177], v[28:31]
	v_mfma_f32_16x16x32_bf16 v[20:23], v[218:221], v[182:185], v[20:23]
	v_mfma_f32_16x16x32_bf16 v[12:15], v[226:229], v[182:185], v[12:15]
	v_mfma_f32_16x16x32_bf16 v[4:7], v[218:221], v[210:213], v[4:7]
	v_mfma_f32_16x16x32_bf16 v[0:3], v[226:229], v[210:213], v[0:3]
	s_barrier
	s_add_i32 s6, 0, 0x18000
	v_add_u32_e32 v146, s6, v206
	ds_read_b128 v[128:131], v146
	ds_read_b128 v[132:135], v146 offset:1024
	ds_read_b128 v[136:139], v146 offset:2048
	ds_read_b128 v[146:149], v146 offset:3072
	s_add_u32 s50, s52, 0xb0000
	s_addc_u32 s51, s53, 0
	s_mov_b32 m0, s68
	v_lshl_add_u64 v[214:215], s[50:51], 0, v[154:155]
	ds_read_b128 v[162:165], v208 offset:32768
	ds_read_b128 v[166:169], v208 offset:33792
	ds_read_b128 v[170:173], v208 offset:34816
	ds_read_b128 v[174:177], v208 offset:35840
	ds_read_b128 v[178:181], v208 offset:36864
	ds_read_b128 v[182:185], v208 offset:37888
	ds_read_b128 v[194:197], v208 offset:38912
	ds_read_b128 v[210:213], v208 offset:39936
	global_load_lds_dwordx4 v[214:215], off
	v_lshl_add_u64 v[214:215], s[50:51], 0, v[152:153]
	s_mov_b32 m0, s69
	s_nop 0
	global_load_lds_dwordx4 v[214:215], off
	s_add_i32 s19, 0, 0x1c000
	v_add_u32_e32 v192, s19, v206
	ds_read_b128 v[214:217], v192
	ds_read_b128 v[218:221], v192 offset:1024
	ds_read_b128 v[222:225], v192 offset:2048
	ds_read_b128 v[226:229], v192 offset:3072
	s_waitcnt vmcnt(8)
	s_waitcnt lgkmcnt(0)
	s_barrier
	v_mfma_f32_16x16x32_bf16 v[124:127], v[128:131], v[162:165], v[124:127]
	v_mfma_f32_16x16x32_bf16 v[120:123], v[136:139], v[162:165], v[120:123]
	v_mfma_f32_16x16x32_bf16 v[108:111], v[128:131], v[170:173], v[108:111]
	v_mfma_f32_16x16x32_bf16 v[104:107], v[136:139], v[170:173], v[104:107]
	v_mfma_f32_16x16x32_bf16 v[96:99], v[128:131], v[178:181], v[96:99]
	v_mfma_f32_16x16x32_bf16 v[88:91], v[136:139], v[178:181], v[88:91]
	v_mfma_f32_16x16x32_bf16 v[84:87], v[128:131], v[194:197], v[84:87]
	v_mfma_f32_16x16x32_bf16 v[80:83], v[136:139], v[194:197], v[80:83]
	v_mfma_f32_16x16x32_bf16 v[124:127], v[132:135], v[166:169], v[124:127]
	v_mfma_f32_16x16x32_bf16 v[120:123], v[146:149], v[166:169], v[120:123]
	v_mfma_f32_16x16x32_bf16 v[108:111], v[132:135], v[174:177], v[108:111]
	v_mfma_f32_16x16x32_bf16 v[104:107], v[146:149], v[174:177], v[104:107]
	v_mfma_f32_16x16x32_bf16 v[96:99], v[132:135], v[182:185], v[96:99]
	v_mfma_f32_16x16x32_bf16 v[88:91], v[146:149], v[182:185], v[88:91]
	v_mfma_f32_16x16x32_bf16 v[84:87], v[132:135], v[210:213], v[84:87]
	v_mfma_f32_16x16x32_bf16 v[80:83], v[146:149], v[210:213], v[80:83]
	v_mfma_f32_16x16x32_bf16 v[116:119], v[214:217], v[162:165], v[116:119]
	v_mfma_f32_16x16x32_bf16 v[112:115], v[222:225], v[162:165], v[112:115]
	v_mfma_f32_16x16x32_bf16 v[100:103], v[214:217], v[170:173], v[100:103]
	v_mfma_f32_16x16x32_bf16 v[92:95], v[222:225], v[170:173], v[92:95]
	v_mfma_f32_16x16x32_bf16 v[76:79], v[214:217], v[178:181], v[76:79]
	v_mfma_f32_16x16x32_bf16 v[72:75], v[222:225], v[178:181], v[72:75]
	v_mfma_f32_16x16x32_bf16 v[68:71], v[214:217], v[194:197], v[68:71]
	v_mfma_f32_16x16x32_bf16 v[64:67], v[222:225], v[194:197], v[64:67]
	v_mfma_f32_16x16x32_bf16 v[116:119], v[218:221], v[166:169], v[116:119]
	v_mfma_f32_16x16x32_bf16 v[112:115], v[226:229], v[166:169], v[112:115]
	v_mfma_f32_16x16x32_bf16 v[100:103], v[218:221], v[174:177], v[100:103]
	v_mfma_f32_16x16x32_bf16 v[92:95], v[226:229], v[174:177], v[92:95]
	v_mfma_f32_16x16x32_bf16 v[76:79], v[218:221], v[182:185], v[76:79]
	v_mfma_f32_16x16x32_bf16 v[72:75], v[226:229], v[182:185], v[72:75]
	v_mfma_f32_16x16x32_bf16 v[68:71], v[218:221], v[210:213], v[68:71]
	v_mfma_f32_16x16x32_bf16 v[64:67], v[226:229], v[210:213], v[64:67]
	s_barrier
	s_add_i32 s6, s6, s57
	v_lshl_add_u64 v[230:231], v[230:231], 0, s[36:37]
	s_mov_b32 m0, s6
	s_nop 0
	global_load_lds_dwordx4 v[230:231], off
	v_lshl_add_u64 v[230:231], v[232:233], 0, s[36:37]
	s_add_i32 m0, s6, 0x2000
	s_nop 0
	global_load_lds_dwordx4 v[230:231], off
	s_mov_b32 m0, s70
	v_lshl_add_u64 v[230:231], v[234:235], 0, s[36:37]
	ds_read_b128 v[162:165], v208 offset:49152
	ds_read_b128 v[166:169], v208 offset:50176
	ds_read_b128 v[170:173], v208 offset:51200
	ds_read_b128 v[174:177], v208 offset:52224
	ds_read_b128 v[178:181], v208 offset:53248
	ds_read_b128 v[182:185], v208 offset:54272
	ds_read_b128 v[194:197], v208 offset:55296
	ds_read_b128 v[210:213], v208 offset:56320
	global_load_lds_dwordx4 v[230:231], off
	v_lshl_add_u64 v[230:231], v[236:237], 0, s[36:37]
	s_mov_b32 m0, s71
	s_nop 0
	global_load_lds_dwordx4 v[230:231], off
	s_add_u32 s48, s48, 0xb0080
	s_addc_u32 s49, s49, 0
	s_add_i32 s6, s19, s57
	v_lshl_add_u64 v[250:251], s[48:49], 0, v[140:141]
	s_mov_b32 m0, s6
	s_nop 0
	global_load_lds_dwordx4 v[250:251], off
	v_lshl_add_u64 v[250:251], s[48:49], 0, v[150:151]
	s_add_i32 m0, s6, 0x2000
	s_nop 0
	global_load_lds_dwordx4 v[250:251], off
	s_waitcnt vmcnt(8)
	s_waitcnt lgkmcnt(0)
	s_barrier
	v_mfma_f32_16x16x32_bf16 v[60:63], v[128:131], v[162:165], v[60:63]
	v_mfma_f32_16x16x32_bf16 v[56:59], v[136:139], v[162:165], v[56:59]
	v_mfma_f32_16x16x32_bf16 v[48:51], v[128:131], v[170:173], v[48:51]
	v_mfma_f32_16x16x32_bf16 v[40:43], v[136:139], v[170:173], v[40:43]
	v_mfma_f32_16x16x32_bf16 v[32:35], v[128:131], v[178:181], v[32:35]
	v_mfma_f32_16x16x32_bf16 v[24:27], v[136:139], v[178:181], v[24:27]
	v_mfma_f32_16x16x32_bf16 v[16:19], v[128:131], v[194:197], v[16:19]
	v_mfma_f32_16x16x32_bf16 v[8:11], v[136:139], v[194:197], v[8:11]
	v_mfma_f32_16x16x32_bf16 v[60:63], v[132:135], v[166:169], v[60:63]
	v_mfma_f32_16x16x32_bf16 v[56:59], v[146:149], v[166:169], v[56:59]
	v_mfma_f32_16x16x32_bf16 v[48:51], v[132:135], v[174:177], v[48:51]
	v_mfma_f32_16x16x32_bf16 v[40:43], v[146:149], v[174:177], v[40:43]
	v_mfma_f32_16x16x32_bf16 v[32:35], v[132:135], v[182:185], v[32:35]
	v_mfma_f32_16x16x32_bf16 v[24:27], v[146:149], v[182:185], v[24:27]
	v_mfma_f32_16x16x32_bf16 v[16:19], v[132:135], v[210:213], v[16:19]
	v_mfma_f32_16x16x32_bf16 v[8:11], v[146:149], v[210:213], v[8:11]
	v_mfma_f32_16x16x32_bf16 v[52:55], v[214:217], v[162:165], v[52:55]
	v_mfma_f32_16x16x32_bf16 v[44:47], v[222:225], v[162:165], v[44:47]
	v_mfma_f32_16x16x32_bf16 v[36:39], v[214:217], v[170:173], v[36:39]
	v_mfma_f32_16x16x32_bf16 v[28:31], v[222:225], v[170:173], v[28:31]
	v_mfma_f32_16x16x32_bf16 v[20:23], v[214:217], v[178:181], v[20:23]
	v_mfma_f32_16x16x32_bf16 v[12:15], v[222:225], v[178:181], v[12:15]
	v_mfma_f32_16x16x32_bf16 v[4:7], v[214:217], v[194:197], v[4:7]
	v_mfma_f32_16x16x32_bf16 v[0:3], v[222:225], v[194:197], v[0:3]
	v_mfma_f32_16x16x32_bf16 v[52:55], v[218:221], v[166:169], v[52:55]
	v_mfma_f32_16x16x32_bf16 v[44:47], v[226:229], v[166:169], v[44:47]
	v_mfma_f32_16x16x32_bf16 v[36:39], v[218:221], v[174:177], v[36:39]
	v_mfma_f32_16x16x32_bf16 v[28:31], v[226:229], v[174:177], v[28:31]
	v_mfma_f32_16x16x32_bf16 v[20:23], v[218:221], v[182:185], v[20:23]
	v_mfma_f32_16x16x32_bf16 v[12:15], v[226:229], v[182:185], v[12:15]
	v_mfma_f32_16x16x32_bf16 v[4:7], v[218:221], v[210:213], v[4:7]
	v_mfma_f32_16x16x32_bf16 v[0:3], v[226:229], v[210:213], v[0:3]
	s_add_i32 s12, s12, 2
	s_add_u32 s10, s10, 0x100
	s_addc_u32 s11, s11, 0
	s_cmp_gt_u32 s12, 41
	s_mov_b64 s[50:51], s[46:47]
	s_barrier
	s_cbranch_scc0 .LBB0_341
	s_mov_b32 s100, 1
	s_ashr_i32 s39, s38, 31
	v_lshl_or_b32 v128, s81, 8, v207
	s_lshl_b64 s[10:11], s[38:39], 8
	v_ashrrev_i32_e32 v129, 31, v128
	v_lshl_add_u64 v[168:169], s[10:11], 0, v[156:157]
	v_lshlrev_b64 v[170:171], 1, v[128:129]
	v_lshl_add_u64 v[174:175], s[26:27], 0, v[170:171]
	v_lshlrev_b64 v[172:173], 11, v[168:169]
	v_lshl_add_u64 v[128:129], v[174:175], 0, v[172:173]
	global_load_dwordx4 v[182:185], v[128:129], off
	global_load_dwordx4 v[210:213], v[128:129], off offset:256
	v_or_b32_e32 v166, 16, v168
	v_mov_b32_e32 v167, v169
	v_lshlrev_b64 v[176:177], 11, v[166:167]
	v_lshl_add_u64 v[128:129], v[174:175], 0, v[176:177]
	global_load_dwordx4 v[214:217], v[128:129], off
	global_load_dwordx4 v[218:221], v[128:129], off offset:256
	v_or_b32_e32 v164, 32, v168
	v_mov_b32_e32 v165, v169
	v_or_b32_e32 v162, 48, v168
	v_mov_b32_e32 v163, v169
	v_lshlrev_b64 v[180:181], 11, v[164:165]
	v_lshlrev_b64 v[178:179], 11, v[162:163]
	v_lshl_add_u64 v[128:129], v[174:175], 0, v[180:181]
	v_lshl_add_u64 v[130:131], v[174:175], 0, v[178:179]
	global_load_dwordx4 v[222:225], v[128:129], off
	global_load_dwordx4 v[136:139], v[128:129], off offset:256
	global_load_dwordx4 v[132:135], v[130:131], off
	s_nop 0
	global_load_dwordx4 v[128:131], v[130:131], off offset:256
	s_mov_b64 s[10:11], 0x90
	v_lshl_add_u64 v[172:173], s[28:29], 0, v[172:173]
	v_lshl_add_u64 v[172:173], v[172:173], 0, v[170:171]
	s_waitcnt vmcnt(0)
	v_lshlrev_b32_e32 v146, 16, v182
	v_and_b32_e32 v147, 0xffff0000, v182
	v_lshlrev_b32_e32 v148, 16, v184
	v_and_b32_e32 v149, 0xffff0000, v184
	v_lshlrev_b32_e32 v182, 16, v183
	v_and_b32_e32 v183, 0xffff0000, v183
	v_lshlrev_b32_e32 v194, 16, v210
	v_and_b32_e32 v195, 0xffff0000, v210
	v_lshlrev_b32_e32 v196, 16, v212
	v_and_b32_e32 v197, 0xffff0000, v212
	v_lshlrev_b32_e32 v210, 16, v211
	v_and_b32_e32 v211, 0xffff0000, v211
	v_lshlrev_b32_e32 v212, 16, v213
	v_and_b32_e32 v213, 0xffff0000, v213
	v_pk_fma_f32 v[124:125], v[124:125], 0.5, v[146:147] op_sel_hi:[1,0,1]
	v_pk_fma_f32 v[120:121], v[120:121], 0.5, v[148:149] op_sel_hi:[1,0,1]
	v_pk_fma_f32 v[126:127], v[126:127], 0.5, v[182:183] op_sel_hi:[1,0,1]
	v_pk_fma_f32 v[116:117], v[116:117], 0.5, v[194:195] op_sel_hi:[1,0,1]
	v_pk_fma_f32 v[146:147], v[112:113], 0.5, v[196:197] op_sel_hi:[1,0,1]
	v_pk_fma_f32 v[118:119], v[118:119], 0.5, v[210:211] op_sel_hi:[1,0,1]
	v_pk_fma_f32 v[148:149], v[114:115], 0.5, v[212:213] op_sel_hi:[1,0,1]
	v_pk_mul_f32 v[212:213], v[124:125], v[124:125]
	v_lshlrev_b32_e32 v182, 16, v214
	v_and_b32_e32 v183, 0xffff0000, v214
	v_lshlrev_b32_e32 v194, 16, v215
	v_and_b32_e32 v195, 0xffff0000, v215
	v_pk_mul_f32 v[214:215], v[126:127], v[126:127]
	v_cvt_pk_bf16_f32 v112, v124, v125
	v_cvt_pk_bf16_f32 v113, v126, v127
	v_pk_mul_f32 v[124:125], v[116:117], v[116:117]
	v_pk_mul_f32 v[126:127], v[118:119], v[118:119]
	v_pk_mul_f32 v[228:229], v[146:147], v[146:147]
	v_cvt_pk_bf16_f32 v116, v116, v117
	v_cvt_pk_bf16_f32 v117, v118, v119
	v_cvt_pk_bf16_f32 v118, v146, v147
	v_add_f32_e32 v146, v212, v213
	v_lshlrev_b32_e32 v184, 16, v185
	v_and_b32_e32 v185, 0xffff0000, v185
	v_add_f32_e32 v146, v214, v146
	v_pk_fma_f32 v[122:123], v[122:123], 0.5, v[184:185] op_sel_hi:[1,0,1]
	v_lshlrev_b32_e32 v184, 16, v216
	v_and_b32_e32 v185, 0xffff0000, v216
	v_lshlrev_b32_e32 v196, 16, v217
	v_and_b32_e32 v197, 0xffff0000, v217
	v_pk_mul_f32 v[216:217], v[120:121], v[120:121]
	v_add_f32_e32 v146, v215, v146
	v_add_f32_e32 v146, v216, v146
	v_pk_mul_f32 v[226:227], v[122:123], v[122:123]
	v_add_f32_e32 v146, v217, v146
	v_add_f32_e32 v146, v226, v146
	v_add_f32_e32 v146, v227, v146
	v_add_f32_e32 v124, v124, v146
	v_add_f32_e32 v124, v125, v124
	v_add_f32_e32 v124, v126, v124
	v_add_f32_e32 v124, v127, v124
	v_add_f32_e32 v124, v228, v124
	v_pk_mul_f32 v[230:231], v[148:149], v[148:149]
	v_add_f32_e32 v124, v229, v124
	v_add_f32_e32 v124, v230, v124
	v_add_f32_e32 v209, v231, v124
	v_lshlrev_b32_e32 v124, 16, v220
	v_and_b32_e32 v125, 0xffff0000, v220
	v_pk_fma_f32 v[124:125], v[92:93], 0.5, v[124:125] op_sel_hi:[1,0,1]
	v_lshlrev_b32_e32 v92, 16, v219
	v_and_b32_e32 v93, 0xffff0000, v219
	v_pk_fma_f32 v[102:103], v[102:103], 0.5, v[92:93] op_sel_hi:[1,0,1]
	v_lshlrev_b32_e32 v92, 16, v221
	v_and_b32_e32 v93, 0xffff0000, v221
	v_pk_fma_f32 v[126:127], v[94:95], 0.5, v[92:93] op_sel_hi:[1,0,1]
	v_lshlrev_b32_e32 v92, 16, v222
	v_and_b32_e32 v93, 0xffff0000, v222
	v_pk_fma_f32 v[92:93], v[96:97], 0.5, v[92:93] op_sel_hi:[1,0,1]
	v_lshlrev_b32_e32 v96, 16, v225
	v_and_b32_e32 v97, 0xffff0000, v225
	v_lshlrev_b32_e32 v94, 16, v224
	v_and_b32_e32 v95, 0xffff0000, v224
	v_pk_fma_f32 v[90:91], v[90:91], 0.5, v[96:97] op_sel_hi:[1,0,1]
	v_lshlrev_b32_e32 v96, 16, v136
	v_and_b32_e32 v97, 0xffff0000, v136
	v_pk_fma_f32 v[88:89], v[88:89], 0.5, v[94:95] op_sel_hi:[1,0,1]
	v_lshlrev_b32_e32 v94, 16, v223
	v_and_b32_e32 v95, 0xffff0000, v223
	v_pk_fma_f32 v[96:97], v[76:77], 0.5, v[96:97] op_sel_hi:[1,0,1]
	v_lshl_add_u64 v[76:77], v[168:169], 0, s[36:37]
	v_cvt_pk_bf16_f32 v114, v120, v121
	v_pk_fma_f32 v[120:121], v[108:109], 0.5, v[182:183] op_sel_hi:[1,0,1]
	v_pk_fma_f32 v[94:95], v[98:99], 0.5, v[94:95] op_sel_hi:[1,0,1]
	v_lshlrev_b64 v[182:183], 11, v[76:77]
	v_lshlrev_b32_e32 v98, 16, v138
	v_and_b32_e32 v99, 0xffff0000, v138
	v_lshl_add_u64 v[146:147], v[174:175], 0, v[182:183]
	v_pk_fma_f32 v[98:99], v[72:73], 0.5, v[98:99] op_sel_hi:[1,0,1]
	v_lshlrev_b32_e32 v72, 16, v137
	v_and_b32_e32 v73, 0xffff0000, v137
	v_lshlrev_b32_e32 v210, 16, v218
	v_and_b32_e32 v211, 0xffff0000, v218
	global_load_dwordx4 v[218:221], v[146:147], off
	global_load_dwordx4 v[226:229], v[146:147], off offset:256
	v_pk_fma_f32 v[136:137], v[78:79], 0.5, v[72:73] op_sel_hi:[1,0,1]
	v_lshlrev_b32_e32 v72, 16, v139
	v_and_b32_e32 v73, 0xffff0000, v139
	v_pk_fma_f32 v[138:139], v[74:75], 0.5, v[72:73] op_sel_hi:[1,0,1]
	v_lshlrev_b32_e32 v72, 16, v132
	v_and_b32_e32 v73, 0xffff0000, v132
	v_pk_fma_f32 v[74:75], v[84:85], 0.5, v[72:73] op_sel_hi:[1,0,1]
	v_lshlrev_b32_e32 v72, 16, v134
	v_and_b32_e32 v73, 0xffff0000, v134
	v_pk_fma_f32 v[78:79], v[80:81], 0.5, v[72:73] op_sel_hi:[1,0,1]
	v_lshlrev_b32_e32 v72, 16, v133
	v_and_b32_e32 v73, 0xffff0000, v133
	v_pk_fma_f32 v[80:81], v[86:87], 0.5, v[72:73] op_sel_hi:[1,0,1]
	v_lshlrev_b32_e32 v72, 16, v135
	v_and_b32_e32 v73, 0xffff0000, v135
	v_pk_fma_f32 v[82:83], v[82:83], 0.5, v[72:73] op_sel_hi:[1,0,1]
	v_lshl_add_u64 v[72:73], v[168:169], 0, s[10:11]
	v_lshlrev_b64 v[132:133], 11, v[72:73]
	v_lshl_add_u64 v[134:135], v[174:175], 0, v[132:133]
	global_load_dwordx4 v[234:237], v[134:135], off
	global_load_dwordx4 v[242:245], v[134:135], off offset:256
	v_lshlrev_b32_e32 v84, 16, v128
	v_and_b32_e32 v85, 0xffff0000, v128
	v_pk_fma_f32 v[84:85], v[68:69], 0.5, v[84:85] op_sel_hi:[1,0,1]
	v_lshlrev_b32_e32 v68, 16, v130
	v_and_b32_e32 v69, 0xffff0000, v130
	v_pk_fma_f32 v[86:87], v[64:65], 0.5, v[68:69] op_sel_hi:[1,0,1]
	v_lshlrev_b32_e32 v64, 16, v129
	v_and_b32_e32 v65, 0xffff0000, v129
	s_mov_b64 s[10:11], 0xa0
	v_pk_fma_f32 v[128:129], v[70:71], 0.5, v[64:65] op_sel_hi:[1,0,1]
	v_lshl_add_u64 v[70:71], v[168:169], 0, s[10:11]
	v_lshlrev_b32_e32 v64, 16, v131
	v_and_b32_e32 v65, 0xffff0000, v131
	v_lshlrev_b64 v[134:135], 11, v[70:71]
	v_pk_fma_f32 v[130:131], v[66:67], 0.5, v[64:65] op_sel_hi:[1,0,1]
	v_lshl_add_u64 v[64:65], v[174:175], 0, v[134:135]
	v_cvt_pk_bf16_f32 v115, v122, v123
	v_pk_fma_f32 v[122:123], v[110:111], 0.5, v[194:195] op_sel_hi:[1,0,1]
	v_pk_fma_f32 v[110:111], v[106:107], 0.5, v[196:197] op_sel_hi:[1,0,1]
	global_load_dwordx4 v[246:249], v[64:65], off
	global_load_dwordx4 v[194:197], v[64:65], off offset:256
	s_mov_b64 s[10:11], 0xb0
	v_lshl_add_u64 v[68:69], v[168:169], 0, s[10:11]
	v_pk_fma_f32 v[108:109], v[104:105], 0.5, v[184:185] op_sel_hi:[1,0,1]
	v_lshlrev_b64 v[184:185], 11, v[68:69]
	v_lshl_add_u64 v[64:65], v[174:175], 0, v[184:185]
	v_cvt_pk_bf16_f32 v119, v148, v149
	global_load_dwordx4 v[146:149], v[64:65], off
	s_nop 0
	global_load_dwordx4 v[64:67], v[64:65], off offset:256
	global_store_dwordx4 v[172:173], v[112:115], off
	global_store_dwordx4 v[172:173], v[116:119], off offset:256
	v_cvt_pk_bf16_f32 v104, v120, v121
	v_lshl_add_u64 v[112:113], s[28:29], 0, v[176:177]
	v_cvt_pk_bf16_f32 v105, v122, v123
	v_cvt_pk_bf16_f32 v106, v108, v109
	v_cvt_pk_bf16_f32 v107, v110, v111
	v_pk_fma_f32 v[100:101], v[100:101], 0.5, v[210:211] op_sel_hi:[1,0,1]
	v_lshl_add_u64 v[112:113], v[112:113], 0, v[170:171]
	v_cvt_pk_bf16_f32 v210, v100, v101
	v_cvt_pk_bf16_f32 v211, v102, v103
	v_cvt_pk_bf16_f32 v212, v124, v125
	v_cvt_pk_bf16_f32 v213, v126, v127
	global_store_dwordx4 v[112:113], v[104:107], off
	global_store_dwordx4 v[112:113], v[210:213], off offset:256
	v_cvt_pk_bf16_f32 v214, v92, v93
	v_lshl_add_u64 v[104:105], s[28:29], 0, v[180:181]
	v_cvt_pk_bf16_f32 v215, v94, v95
	v_cvt_pk_bf16_f32 v216, v88, v89
	v_cvt_pk_bf16_f32 v217, v90, v91
	v_lshl_add_u64 v[104:105], v[104:105], 0, v[170:171]
	v_cvt_pk_bf16_f32 v222, v96, v97
	v_cvt_pk_bf16_f32 v223, v136, v137
	v_cvt_pk_bf16_f32 v224, v98, v99
	v_cvt_pk_bf16_f32 v225, v138, v139
	global_store_dwordx4 v[104:105], v[214:217], off
	global_store_dwordx4 v[104:105], v[222:225], off offset:256
	v_lshl_add_u64 v[104:105], s[28:29], 0, v[178:179]
	v_cvt_pk_bf16_f32 v230, v74, v75
	v_cvt_pk_bf16_f32 v231, v80, v81
	v_cvt_pk_bf16_f32 v232, v78, v79
	v_cvt_pk_bf16_f32 v233, v82, v83
	v_lshl_add_u64 v[104:105], v[104:105], 0, v[170:171]
	v_cvt_pk_bf16_f32 v238, v84, v85
	v_cvt_pk_bf16_f32 v239, v128, v129
	v_cvt_pk_bf16_f32 v240, v86, v87
	v_cvt_pk_bf16_f32 v241, v130, v131
	global_store_dwordx4 v[104:105], v[230:233], off
	global_store_dwordx4 v[104:105], v[238:241], off offset:256
	s_waitcnt vmcnt(8)
	v_lshlrev_b32_e32 v104, 16, v218
	v_and_b32_e32 v105, 0xffff0000, v218
	v_pk_fma_f32 v[60:61], v[60:61], 0.5, v[104:105] op_sel_hi:[1,0,1]
	v_lshlrev_b32_e32 v104, 16, v220
	v_and_b32_e32 v105, 0xffff0000, v220
	v_pk_fma_f32 v[56:57], v[56:57], 0.5, v[104:105] op_sel_hi:[1,0,1]
	v_lshlrev_b32_e32 v104, 16, v219
	v_and_b32_e32 v105, 0xffff0000, v219
	v_pk_fma_f32 v[62:63], v[62:63], 0.5, v[104:105] op_sel_hi:[1,0,1]
	v_lshlrev_b32_e32 v104, 16, v221
	v_and_b32_e32 v105, 0xffff0000, v221
	v_pk_fma_f32 v[58:59], v[58:59], 0.5, v[104:105] op_sel_hi:[1,0,1]
	v_lshlrev_b32_e32 v104, 16, v226
	v_and_b32_e32 v105, 0xffff0000, v226
	v_pk_fma_f32 v[52:53], v[52:53], 0.5, v[104:105] op_sel_hi:[1,0,1]
	v_lshlrev_b32_e32 v104, 16, v228
	v_and_b32_e32 v105, 0xffff0000, v228
	v_pk_fma_f32 v[104:105], v[44:45], 0.5, v[104:105] op_sel_hi:[1,0,1]
	v_lshlrev_b32_e32 v44, 16, v227
	v_and_b32_e32 v45, 0xffff0000, v227
	v_pk_fma_f32 v[54:55], v[54:55], 0.5, v[44:45] op_sel_hi:[1,0,1]
	v_lshlrev_b32_e32 v44, 16, v229
	v_and_b32_e32 v45, 0xffff0000, v229
	v_pk_fma_f32 v[106:107], v[46:47], 0.5, v[44:45] op_sel_hi:[1,0,1]
	v_lshlrev_b32_e32 v44, 16, v234
	v_and_b32_e32 v45, 0xffff0000, v234
	v_pk_fma_f32 v[44:45], v[48:49], 0.5, v[44:45] op_sel_hi:[1,0,1]
	v_lshlrev_b32_e32 v48, 16, v237
	v_and_b32_e32 v49, 0xffff0000, v237
	v_pk_fma_f32 v[42:43], v[42:43], 0.5, v[48:49] op_sel_hi:[1,0,1]
	v_lshlrev_b32_e32 v48, 16, v242
	v_and_b32_e32 v49, 0xffff0000, v242
	v_pk_fma_f32 v[36:37], v[36:37], 0.5, v[48:49] op_sel_hi:[1,0,1]
	v_lshlrev_b32_e32 v48, 16, v244
	v_and_b32_e32 v49, 0xffff0000, v244
	v_lshlrev_b32_e32 v46, 16, v236
	v_and_b32_e32 v47, 0xffff0000, v236
	v_pk_fma_f32 v[48:49], v[28:29], 0.5, v[48:49] op_sel_hi:[1,0,1]
	v_lshlrev_b32_e32 v28, 16, v243
	v_and_b32_e32 v29, 0xffff0000, v243
	v_pk_fma_f32 v[40:41], v[40:41], 0.5, v[46:47] op_sel_hi:[1,0,1]
	v_lshlrev_b32_e32 v46, 16, v235
	v_and_b32_e32 v47, 0xffff0000, v235
	v_pk_fma_f32 v[38:39], v[38:39], 0.5, v[28:29] op_sel_hi:[1,0,1]
	v_lshlrev_b32_e32 v28, 16, v245
	v_and_b32_e32 v29, 0xffff0000, v245
	v_pk_fma_f32 v[46:47], v[50:51], 0.5, v[46:47] op_sel_hi:[1,0,1]
	v_pk_fma_f32 v[50:51], v[30:31], 0.5, v[28:29] op_sel_hi:[1,0,1]
	v_lshlrev_b32_e32 v28, 16, v246
	v_and_b32_e32 v29, 0xffff0000, v246
	v_pk_fma_f32 v[28:29], v[32:33], 0.5, v[28:29] op_sel_hi:[1,0,1]
	v_lshlrev_b32_e32 v32, 16, v249
	v_and_b32_e32 v33, 0xffff0000, v249
	v_pk_fma_f32 v[26:27], v[26:27], 0.5, v[32:33] op_sel_hi:[1,0,1]
	v_lshlrev_b32_e32 v32, 16, v194
	v_and_b32_e32 v33, 0xffff0000, v194
	v_pk_fma_f32 v[20:21], v[20:21], 0.5, v[32:33] op_sel_hi:[1,0,1]
	v_lshlrev_b32_e32 v32, 16, v196
	v_and_b32_e32 v33, 0xffff0000, v196
	v_lshlrev_b32_e32 v30, 16, v248
	v_and_b32_e32 v31, 0xffff0000, v248
	v_pk_fma_f32 v[32:33], v[12:13], 0.5, v[32:33] op_sel_hi:[1,0,1]
	v_lshlrev_b32_e32 v12, 16, v195
	v_and_b32_e32 v13, 0xffff0000, v195
	v_pk_fma_f32 v[24:25], v[24:25], 0.5, v[30:31] op_sel_hi:[1,0,1]
	v_lshlrev_b32_e32 v30, 16, v247
	v_and_b32_e32 v31, 0xffff0000, v247
	v_pk_fma_f32 v[22:23], v[22:23], 0.5, v[12:13] op_sel_hi:[1,0,1]
	v_lshlrev_b32_e32 v12, 16, v197
	v_and_b32_e32 v13, 0xffff0000, v197
	v_pk_fma_f32 v[30:31], v[34:35], 0.5, v[30:31] op_sel_hi:[1,0,1]
	v_pk_fma_f32 v[34:35], v[14:15], 0.5, v[12:13] op_sel_hi:[1,0,1]
	v_lshlrev_b32_e32 v14, 16, v148
	v_and_b32_e32 v15, 0xffff0000, v148
	v_lshlrev_b32_e32 v12, 16, v146
	v_and_b32_e32 v13, 0xffff0000, v146
	v_pk_fma_f32 v[8:9], v[8:9], 0.5, v[14:15] op_sel_hi:[1,0,1]
	v_lshlrev_b32_e32 v14, 16, v147
	v_and_b32_e32 v15, 0xffff0000, v147
	v_lshlrev_b32_e32 v146, 16, v64
	v_and_b32_e32 v147, 0xffff0000, v64
	v_pk_fma_f32 v[4:5], v[4:5], 0.5, v[146:147] op_sel_hi:[1,0,1]
	v_lshlrev_b32_e32 v146, 16, v66
	v_and_b32_e32 v147, 0xffff0000, v66
	v_pk_fma_f32 v[0:1], v[0:1], 0.5, v[146:147] op_sel_hi:[1,0,1]
	v_lshl_add_u64 v[146:147], s[28:29], 0, v[182:183]
	v_cvt_pk_bf16_f32 v112, v60, v61
	v_cvt_pk_bf16_f32 v113, v62, v63
	v_cvt_pk_bf16_f32 v114, v56, v57
	v_cvt_pk_bf16_f32 v115, v58, v59
	v_lshl_add_u64 v[146:147], v[146:147], 0, v[170:171]
	v_cvt_pk_bf16_f32 v116, v52, v53
	v_cvt_pk_bf16_f32 v117, v54, v55
	v_cvt_pk_bf16_f32 v118, v104, v105
	v_cvt_pk_bf16_f32 v119, v106, v107
	global_store_dwordx4 v[146:147], v[112:115], off
	global_store_dwordx4 v[146:147], v[116:119], off offset:256
	v_cvt_pk_bf16_f32 v172, v44, v45
	v_lshl_add_u64 v[112:113], s[28:29], 0, v[132:133]
	v_cvt_pk_bf16_f32 v173, v46, v47
	v_cvt_pk_bf16_f32 v174, v40, v41
	v_cvt_pk_bf16_f32 v175, v42, v43
	v_lshl_add_u64 v[112:113], v[112:113], 0, v[170:171]
	v_cvt_pk_bf16_f32 v176, v36, v37
	v_cvt_pk_bf16_f32 v177, v38, v39
	v_cvt_pk_bf16_f32 v178, v48, v49
	v_cvt_pk_bf16_f32 v179, v50, v51
	global_store_dwordx4 v[112:113], v[172:175], off
	global_store_dwordx4 v[112:113], v[176:179], off offset:256
	v_lshl_add_u64 v[112:113], s[28:29], 0, v[134:135]
	v_cvt_pk_bf16_f32 v210, v28, v29
	v_cvt_pk_bf16_f32 v211, v30, v31
	v_cvt_pk_bf16_f32 v212, v24, v25
	v_cvt_pk_bf16_f32 v213, v26, v27
	v_pk_fma_f32 v[12:13], v[16:17], 0.5, v[12:13] op_sel_hi:[1,0,1]
	v_lshlrev_b32_e32 v16, 16, v149
	v_and_b32_e32 v17, 0xffff0000, v149
	v_lshlrev_b32_e32 v64, 16, v65
	v_and_b32_e32 v65, 0xffff0000, v65
	v_lshl_add_u64 v[112:113], v[112:113], 0, v[170:171]
	v_cvt_pk_bf16_f32 v194, v20, v21
	v_cvt_pk_bf16_f32 v195, v22, v23
	v_cvt_pk_bf16_f32 v196, v32, v33
	v_cvt_pk_bf16_f32 v197, v34, v35
	v_pk_fma_f32 v[14:15], v[18:19], 0.5, v[14:15] op_sel_hi:[1,0,1]
	v_pk_fma_f32 v[10:11], v[10:11], 0.5, v[16:17] op_sel_hi:[1,0,1]
	v_pk_fma_f32 v[6:7], v[6:7], 0.5, v[64:65] op_sel_hi:[1,0,1]
	v_lshlrev_b32_e32 v64, 16, v67
	v_and_b32_e32 v65, 0xffff0000, v67
	global_store_dwordx4 v[112:113], v[210:213], off
	global_store_dwordx4 v[112:113], v[194:197], off offset:256
	v_lshl_add_u64 v[112:113], s[28:29], 0, v[184:185]
	v_cvt_pk_bf16_f32 v16, v12, v13
	v_cvt_pk_bf16_f32 v17, v14, v15
	v_cvt_pk_bf16_f32 v18, v8, v9
	v_cvt_pk_bf16_f32 v19, v10, v11
	v_pk_fma_f32 v[2:3], v[2:3], 0.5, v[64:65] op_sel_hi:[1,0,1]
	v_lshl_add_u64 v[112:113], v[112:113], 0, v[170:171]
	v_cvt_pk_bf16_f32 v64, v4, v5
	v_cvt_pk_bf16_f32 v65, v6, v7
	v_cvt_pk_bf16_f32 v66, v0, v1
	v_cvt_pk_bf16_f32 v67, v2, v3
	global_store_dwordx4 v[112:113], v[16:19], off
	global_store_dwordx4 v[112:113], v[64:67], off offset:256
	s_lshl_b32 s10, s81, 2
	v_and_b32_e32 v17, 64, v188
	v_xor_b32_e32 v16, 16, v188
	v_add_u32_e32 v17, 64, v17
	v_cmp_lt_i32_e32 vcc, v16, v17
	v_xor_b32_e32 v18, 32, v188
	s_ashr_i32 s11, s10, 31
	v_cndmask_b32_e32 v16, v188, v16, vcc
	v_lshlrev_b32_e32 v16, 2, v16
	ds_bpermute_b32 v19, v16, v209
	v_cmp_lt_i32_e32 vcc, v18, v17
	s_lshl_b64 s[10:11], s[10:11], 2
	s_add_u32 s38, s73, s10
	v_cndmask_b32_e32 v17, v188, v18, vcc
	v_lshlrev_b32_e32 v17, 2, v17
	s_waitcnt lgkmcnt(0)
	v_add_f32_e32 v18, v209, v19
	ds_bpermute_b32 v19, v17, v18
	s_addc_u32 s39, s74, s11
	s_and_saveexec_b64 s[46:47], s[42:43]
	s_cbranch_execz .LBB0_344
	s_waitcnt lgkmcnt(0)
	v_add_f32_e32 v64, v18, v19
	v_lshlrev_b64 v[18:19], 6, v[168:169]
	v_lshl_add_u64 v[18:19], s[38:39], 0, v[18:19]
	global_store_dword v[18:19], v64, off
